# next-layer latent pre-norm fused into down-proj phase tail on idle workgroups 128..255 (per-XCD release counter, wave-group skew safe)
# baseline (speedup 1.0000x reference)
; __device__ __forceinline__ int obid() { int b = blockIdx.x; asm volatile("" : "+s"(b)); return b; }
; #define PN_LOAD(dst, rw) do { const float* s_ = (rw) < NLAT ? hlat + (size_t)(rw) * 1024 : hctx + (size_t)((rw) - NLAT) * 1024; \
;         _Pragma("unroll") for (int i = 0; i < 4; ++i) dst[i] = *(const float4*)(s_ + i * 256 + lane * 4); } while (0)
; __device__ __forceinline__ void p_norm(const float* hlat, const float* hctx, const float* g, const float* modl, int sh_off, int sc_off, bf16_t* A, int M,
;                                        const float* part, const float* cgate, float* hcout) {
;     ...
;     int row = obid() * 8 + wave;
;     float4 v[4], nv[4];
;     ...
;     if (row < M) PN_LOAD(v, row);
;     while (row < M) {
;         const int nrow = row + stride;
;         if (nrow < M) PN_LOAD(nv, nrow);
;         const int r = row < NLAT ? (row >> 11) : 16;
;         float ss = 0.f;
; #pragma unroll
;         for (int i = 0; i < 4; ++i) {
;             if (part != nullptr && row >= NLAT) {
;                 const size_t po = (size_t)(row - NLAT) * 1024 + i * 256 + lane * 4;
;                 const float4 p0 = *(const float4*)(part + po), p1 = *(const float4*)(part + (size_t)4096 * 1024 + po), cg = *(const float4*)(cgate + i * 256 + lane * 4);
;                 v[i].x += cg.x * (p0.x + p1.x); v[i].y += cg.y * (p0.y + p1.y); v[i].z += cg.z * (p0.z + p1.z); v[i].w += cg.w * (p0.w + p1.w);
;                 *(float4*)(hcout + po) = v[i];
;             }
;             ss += v[i].x * v[i].x + v[i].y * v[i].y + v[i].z * v[i].z + v[i].w * v[i].w; }
;         ss = wave_sum(ss);
.LBB0_406:
	s_load_dwordx2 s[6:7], s[16:17], 0x0
	s_mul_hi_u32 s5, s8, 0x66000
	s_mov_b32 s9, s55
	v_mov_b32_e32 v14, v253
	s_waitcnt lgkmcnt(0)
	v_writelane_b32 v255, s6, 41
	v_ashrrev_i32_e32 v1, 6, v14
	s_nop 0
	v_writelane_b32 v255, s7, 42
	s_mul_i32 s6, s8, 0x66000
	s_add_u32 s6, s56, s6
	s_addc_u32 s7, s57, s5
	v_writelane_b32 v255, s6, 43
	s_mov_b32 s5, s63
	s_lshl_b32 s5, s5, 3
	v_writelane_b32 v255, s7, 44
	v_writelane_b32 v255, s8, 45
	s_lshl_b32 s6, s8, 10
	s_mov_b32 s7, s55
	v_writelane_b32 v255, s9, 46
	v_writelane_b32 v255, s6, 47
	v_add_u32_e32 v50, s5, v1
	s_waitcnt vmcnt(0) lgkmcnt(0)
	v_readlane_b32 s100, v255, 45
	s_load_dwordx2 s[48:49], s[0:1], 0x30
	s_cmp_eq_u32 s100, 0
	s_cselect_b32 s101, 0, 0xe8
	s_load_dwordx2 s[46:47], s[0:1], s101
	s_load_dwordx2 s[16:17], s[0:1], 0x10
	s_mul_i32 s101, s100, 0x66000
	s_add_u32 s50, s56, s101
	s_addc_u32 s51, s57, 0
	s_sub_u32 s20, s101, 0x66000
	s_cmp_eq_u32 s100, 0
	s_cselect_b32 s20, 0, s20
	s_add_u32 s20, s20, 0x65000
	s_add_u32 s20, s56, s20
	s_addc_u32 s21, s57, 0
	s_add_u32 s98, s50, 0x1000
	s_addc_u32 s99, s51, 0
	s_lshl_b32 s101, s100, 12
	v_and_b32_e32 v240, 63, v253
	v_lshlrev_b32_e32 v241, 4, v240
	v_lshrrev_b32_e32 v148, 7, v50
	v_lshlrev_b32_e32 v146, 4, v50
	v_lshl_add_u32 v144, v146, 12, v241
	v_lshlrev_b32_e32 v146, 11, v146
	v_lshl_add_u32 v146, v240, 3, v146
	v_mul_u32_u24_e32 v148, 0x6000, v148
	v_add_u32_e32 v148, v148, v241
	s_waitcnt lgkmcnt(0)
	s_add_u32 s48, s48, s101
	s_addc_u32 s49, s49, 0
	s_cmp_eq_u32 s100, 0
	s_cselect_b32 s16, s16, s64
	s_cselect_b32 s17, s17, s65
	s_cmp_eq_u32 s100, 0
	s_cbranch_scc1 .Lnorm_P1_alt
	v_lshl_add_u32 v144, v50, 13, v241
	v_mov_b32_e32 v152, v144
	v_add_u32_e32 v150, 0x1000000, v144
	global_load_dwordx4 v[156:159], v144, s[16:17]
	global_load_dwordx4 v[160:163], v144, s[16:17] offset:1024
	global_load_dwordx4 v[164:167], v144, s[16:17] offset:2048
	global_load_dwordx4 v[168:171], v144, s[16:17] offset:3072
	v_add_u32_e32 v144, 0x1000, v144
	v_add_u32_e32 v151, 0x60000, v241
	global_load_dwordx4 v[34:37], v151, s[98:99]
	global_load_dwordx4 v[38:41], v151, s[98:99] offset:1024
	global_load_dwordx4 v[42:45], v151, s[98:99] offset:2048
	global_load_dwordx4 v[46:49], v151, s[98:99] offset:3072
	global_load_dwordx4 v[224:227], v151, s[50:51]
	global_load_dwordx4 v[228:231], v151, s[50:51] offset:1024
	global_load_dwordx4 v[232:235], v151, s[50:51] offset:2048
	global_load_dwordx4 v[236:239], v151, s[50:51] offset:3072
	global_load_dwordx4 v[188:191], v241, s[48:49]
	global_load_dwordx4 v[192:195], v241, s[48:49] offset:1024
	global_load_dwordx4 v[196:199], v241, s[48:49] offset:2048
	global_load_dwordx4 v[200:203], v241, s[48:49] offset:3072
	global_load_dwordx4 v[172:175], v144, s[16:17]
	global_load_dwordx4 v[176:179], v144, s[16:17] offset:1024
	global_load_dwordx4 v[180:183], v144, s[16:17] offset:2048
	global_load_dwordx4 v[184:187], v144, s[16:17] offset:3072
	v_add_u32_e32 v144, 0x1000, v144
	global_load_dwordx4 v[8:11], v241, s[20:21]
	global_load_dwordx4 v[52:55], v241, s[20:21] offset:1024
	global_load_dwordx4 v[60:63], v241, s[20:21] offset:2048
	global_load_dwordx4 v[64:67], v241, s[20:21] offset:3072
	global_load_dwordx4 v[80:83], v152, s[70:71]
	global_load_dwordx4 v[84:87], v152, s[70:71] offset:1024
	global_load_dwordx4 v[88:91], v152, s[70:71] offset:2048
	global_load_dwordx4 v[92:95], v152, s[70:71] offset:3072
	global_load_dwordx4 v[96:99], v150, s[70:71]
	global_load_dwordx4 v[100:103], v150, s[70:71] offset:1024
	global_load_dwordx4 v[104:107], v150, s[70:71] offset:2048
	global_load_dwordx4 v[108:111], v150, s[70:71] offset:3072
	v_add_u32_e32 v207, 0x1000, v152
	global_load_dwordx4 v[112:115], v207, s[70:71]
	global_load_dwordx4 v[116:119], v207, s[70:71] offset:1024
	global_load_dwordx4 v[120:123], v207, s[70:71] offset:2048
	global_load_dwordx4 v[124:127], v207, s[70:71] offset:3072
	v_add_u32_e32 v207, 0x1000, v150
	global_load_dwordx4 v[128:131], v207, s[70:71]
	global_load_dwordx4 v[132:135], v207, s[70:71] offset:1024
	global_load_dwordx4 v[136:139], v207, s[70:71] offset:2048
	global_load_dwordx4 v[140:143], v207, s[70:71] offset:3072
	s_waitcnt vmcnt(8)
	v_pk_add_f32 v[80:81], v[80:81], v[96:97]
	v_pk_add_f32 v[82:83], v[82:83], v[98:99]
	v_pk_fma_f32 v[156:157], v[80:81], v[8:9], v[156:157]
	v_pk_fma_f32 v[158:159], v[82:83], v[10:11], v[158:159]
	global_store_dwordx4 v152, v[156:159], s[64:65]
	v_pk_add_f32 v[84:85], v[84:85], v[100:101]
	v_pk_add_f32 v[86:87], v[86:87], v[102:103]
	v_pk_fma_f32 v[160:161], v[84:85], v[52:53], v[160:161]
	v_pk_fma_f32 v[162:163], v[86:87], v[54:55], v[162:163]
	global_store_dwordx4 v152, v[160:163], s[64:65] offset:1024
	v_pk_add_f32 v[88:89], v[88:89], v[104:105]
	v_pk_add_f32 v[90:91], v[90:91], v[106:107]
	v_pk_fma_f32 v[164:165], v[88:89], v[60:61], v[164:165]
	v_pk_fma_f32 v[166:167], v[90:91], v[62:63], v[166:167]
	global_store_dwordx4 v152, v[164:167], s[64:65] offset:2048
	v_pk_add_f32 v[92:93], v[92:93], v[108:109]
	v_pk_add_f32 v[94:95], v[94:95], v[110:111]
	v_pk_fma_f32 v[168:169], v[92:93], v[64:65], v[168:169]
	v_pk_fma_f32 v[170:171], v[94:95], v[66:67], v[170:171]
	global_store_dwordx4 v152, v[168:171], s[64:65] offset:3072
	v_add_u32_e32 v152, 0x1000, v152
	v_pk_mul_f32 v[242:243], v[156:157], v[156:157]
	v_pk_mul_f32 v[244:245], v[160:161], v[160:161]
	v_pk_mul_f32 v[246:247], v[158:159], v[158:159]
	v_pk_mul_f32 v[248:249], v[162:163], v[162:163]
	v_add_f32_e32 v204, v245, v244
	v_add_f32_e32 v205, v243, v242
	v_add_f32_e32 v204, v248, v204
	v_add_f32_e32 v205, v246, v205
	v_add_f32_e32 v204, v249, v204
	v_add_f32_e32 v205, v247, v205
	v_pk_mul_f32 v[242:243], v[164:165], v[164:165]
	v_pk_mul_f32 v[244:245], v[168:169], v[168:169]
	v_pk_mul_f32 v[246:247], v[166:167], v[166:167]
	v_pk_mul_f32 v[248:249], v[170:171], v[170:171]
	v_add_f32_e32 v206, v243, v242
	v_add_f32_e32 v207, v245, v244
	v_add_f32_e32 v206, v246, v206
	v_add_f32_e32 v207, v248, v207
	v_add_f32_e32 v206, v247, v206
	v_add_f32_e32 v207, v249, v207
	v_add_f32_e32 v204, v205, v204
	v_add_f32_e32 v204, v204, v206
	v_add_f32_e32 v204, v204, v207
	ds_swizzle_b32 v205, v204 offset:swizzle(SWAP,1)
	s_waitcnt lgkmcnt(0)
; __device__ __forceinline__ unsigned pk2(float lo, float hi) { const g_f32x2 f = {lo, hi}; return __builtin_bit_cast(unsigned, __builtin_convertvector(f, g_bf16x2)); }
; __device__ __forceinline__ void p_norm(const float* hlat, const float* hctx, const float* g, const float* modl, int sh_off, int sc_off, bf16_t* A, int M,
;                                        const float* part, const float* cgate, float* hcout) {
;     ...
;             ss += v[i].x * v[i].x + v[i].y * v[i].y + v[i].z * v[i].z + v[i].w * v[i].w; }
;         ss = wave_sum(ss);
;         const float rstd = rsqrtf(ss * (1.0f / 1024.0f) + EPS);
;         const float* mr = modl + (size_t)r * 6144;
; #pragma unroll
;         for (int i = 0; i < 4; ++i) {
;             const int k = i * 256 + lane * 4;
;             const float4 gg = *(const float4*)(g + k), scv = *(const float4*)(mr + sc_off + k), shv = *(const float4*)(mr + sh_off + k);
;             const float o0 = v[i].x * rstd * gg.x * (1.0f + scv.x) + shv.x, o1 = v[i].y * rstd * gg.y * (1.0f + scv.y) + shv.y;
;             const float o2 = v[i].z * rstd * gg.z * (1.0f + scv.z) + shv.z, o3 = v[i].w * rstd * gg.w * (1.0f + scv.w) + shv.w;
;             uint2 w; w.x = pk2(o0, o1); w.y = pk2(o2, o3);
;             *(uint2*)(A + (size_t)row * 1024 + k) = w;
;         }
	v_add_f32_e32 v204, v204, v205
	ds_swizzle_b32 v205, v204 offset:swizzle(SWAP,2)
	s_waitcnt lgkmcnt(0)
	v_add_f32_e32 v204, v204, v205
	ds_swizzle_b32 v205, v204 offset:swizzle(SWAP,4)
	s_waitcnt lgkmcnt(0)
	v_add_f32_e32 v204, v204, v205
	ds_swizzle_b32 v205, v204 offset:swizzle(SWAP,8)
	s_waitcnt lgkmcnt(0)
	v_add_f32_e32 v204, v204, v205
	ds_swizzle_b32 v205, v204 offset:swizzle(SWAP,16)
	s_waitcnt lgkmcnt(0)
	v_add_f32_e32 v204, v204, v205
	v_mov_b32_e32 v205, v204
	s_nop 1
	v_permlane32_swap_b32_e32 v204, v205
	v_add_f32_e32 v204, v204, v205
	v_mov_b32_e32 v205, 0x358637bd
	v_fmamk_f32 v204, v204, 0x3a800000, v205
	v_rsq_f32_e32 v204, v204
	s_nop 0
	v_pk_add_f32 v[34:35], v[34:35], 1.0 op_sel_hi:[1,0]
	v_pk_add_f32 v[36:37], v[36:37], 1.0 op_sel_hi:[1,0]
	v_pk_add_f32 v[38:39], v[38:39], 1.0 op_sel_hi:[1,0]
	v_pk_add_f32 v[40:41], v[40:41], 1.0 op_sel_hi:[1,0]
	v_pk_add_f32 v[42:43], v[42:43], 1.0 op_sel_hi:[1,0]
	v_pk_add_f32 v[44:45], v[44:45], 1.0 op_sel_hi:[1,0]
	v_pk_add_f32 v[46:47], v[46:47], 1.0 op_sel_hi:[1,0]
	v_pk_add_f32 v[48:49], v[48:49], 1.0 op_sel_hi:[1,0]
	v_lshlrev_b32_e32 v146, 12, v50
	v_lshl_add_u32 v146, v240, 3, v146
	v_add_u32_e32 v146, 0x4000000, v146
	v_pk_mul_f32 v[156:157], v[156:157], v[204:205] op_sel_hi:[1,0]
	v_pk_mul_f32 v[158:159], v[158:159], v[204:205] op_sel_hi:[1,0]
	v_pk_mul_f32 v[156:157], v[188:189], v[156:157]
	v_pk_mul_f32 v[158:159], v[190:191], v[158:159]
	v_pk_fma_f32 v[156:157], v[34:35], v[156:157], v[224:225]
	v_pk_fma_f32 v[158:159], v[36:37], v[158:159], v[226:227]
	v_cvt_pk_bf16_f32 v156, v156, v157
	v_cvt_pk_bf16_f32 v157, v158, v159
	global_store_dwordx2 v146, v[156:157], s[66:67]
	v_pk_mul_f32 v[160:161], v[160:161], v[204:205] op_sel_hi:[1,0]
	v_pk_mul_f32 v[162:163], v[162:163], v[204:205] op_sel_hi:[1,0]
	v_pk_mul_f32 v[160:161], v[192:193], v[160:161]
	v_pk_mul_f32 v[162:163], v[194:195], v[162:163]
	v_pk_fma_f32 v[160:161], v[38:39], v[160:161], v[228:229]
	v_pk_fma_f32 v[162:163], v[40:41], v[162:163], v[230:231]
	v_cvt_pk_bf16_f32 v160, v160, v161
	v_cvt_pk_bf16_f32 v161, v162, v163
	global_store_dwordx2 v146, v[160:161], s[66:67] offset:512
	v_pk_mul_f32 v[164:165], v[164:165], v[204:205] op_sel_hi:[1,0]
	v_pk_mul_f32 v[166:167], v[166:167], v[204:205] op_sel_hi:[1,0]
	v_pk_mul_f32 v[164:165], v[196:197], v[164:165]
	v_pk_mul_f32 v[166:167], v[198:199], v[166:167]
	v_pk_fma_f32 v[164:165], v[42:43], v[164:165], v[232:233]
	v_pk_fma_f32 v[166:167], v[44:45], v[166:167], v[234:235]
	v_cvt_pk_bf16_f32 v164, v164, v165
	v_cvt_pk_bf16_f32 v165, v166, v167
	global_store_dwordx2 v146, v[164:165], s[66:67] offset:1024
	v_pk_mul_f32 v[168:169], v[168:169], v[204:205] op_sel_hi:[1,0]
	v_pk_mul_f32 v[170:171], v[170:171], v[204:205] op_sel_hi:[1,0]
	v_pk_mul_f32 v[168:169], v[200:201], v[168:169]
	v_pk_mul_f32 v[170:171], v[202:203], v[170:171]
	v_pk_fma_f32 v[168:169], v[46:47], v[168:169], v[236:237]
	v_pk_fma_f32 v[170:171], v[48:49], v[170:171], v[238:239]
	v_cvt_pk_bf16_f32 v168, v168, v169
	v_cvt_pk_bf16_f32 v169, v170, v171
	global_store_dwordx2 v146, v[168:169], s[66:67] offset:1536
	v_add_u32_e32 v146, 0x800, v146
	s_waitcnt vmcnt(8)
; __device__ __forceinline__ unsigned pk2(float lo, float hi) { const g_f32x2 f = {lo, hi}; return __builtin_bit_cast(unsigned, __builtin_convertvector(f, g_bf16x2)); }
; __device__ __forceinline__ void p_norm(const float* hlat, const float* hctx, const float* g, const float* modl, int sh_off, int sc_off, bf16_t* A, int M,
;                                        const float* part, const float* cgate, float* hcout) {
;     ...
;             if (part != nullptr && row >= NLAT) {
;                 const size_t po = (size_t)(row - NLAT) * 1024 + i * 256 + lane * 4;
;                 const float4 p0 = *(const float4*)(part + po), p1 = *(const float4*)(part + (size_t)4096 * 1024 + po), cg = *(const float4*)(cgate + i * 256 + lane * 4);
;                 v[i].x += cg.x * (p0.x + p1.x); v[i].y += cg.y * (p0.y + p1.y); v[i].z += cg.z * (p0.z + p1.z); v[i].w += cg.w * (p0.w + p1.w);
;                 *(float4*)(hcout + po) = v[i];
;             }
;             ss += v[i].x * v[i].x + v[i].y * v[i].y + v[i].z * v[i].z + v[i].w * v[i].w; }
;         ss = wave_sum(ss);
;         const float rstd = rsqrtf(ss * (1.0f / 1024.0f) + EPS);
;         const float* mr = modl + (size_t)r * 6144;
; #pragma unroll
;         for (int i = 0; i < 4; ++i) {
;             const int k = i * 256 + lane * 4;
;             const float4 gg = *(const float4*)(g + k), scv = *(const float4*)(mr + sc_off + k), shv = *(const float4*)(mr + sh_off + k);
;             const float o0 = v[i].x * rstd * gg.x * (1.0f + scv.x) + shv.x, o1 = v[i].y * rstd * gg.y * (1.0f + scv.y) + shv.y;
;             const float o2 = v[i].z * rstd * gg.z * (1.0f + scv.z) + shv.z, o3 = v[i].w * rstd * gg.w * (1.0f + scv.w) + shv.w;
;             uint2 w; w.x = pk2(o0, o1); w.y = pk2(o2, o3);
;             *(uint2*)(A + (size_t)row * 1024 + k) = w;
;         }
	v_pk_add_f32 v[112:113], v[112:113], v[128:129]
	v_pk_add_f32 v[114:115], v[114:115], v[130:131]
	v_pk_fma_f32 v[172:173], v[112:113], v[8:9], v[172:173]
	v_pk_fma_f32 v[174:175], v[114:115], v[10:11], v[174:175]
	global_store_dwordx4 v152, v[172:175], s[64:65]
	v_pk_add_f32 v[116:117], v[116:117], v[132:133]
	v_pk_add_f32 v[118:119], v[118:119], v[134:135]
	v_pk_fma_f32 v[176:177], v[116:117], v[52:53], v[176:177]
	v_pk_fma_f32 v[178:179], v[118:119], v[54:55], v[178:179]
	global_store_dwordx4 v152, v[176:179], s[64:65] offset:1024
	v_pk_add_f32 v[120:121], v[120:121], v[136:137]
	v_pk_add_f32 v[122:123], v[122:123], v[138:139]
	v_pk_fma_f32 v[180:181], v[120:121], v[60:61], v[180:181]
	v_pk_fma_f32 v[182:183], v[122:123], v[62:63], v[182:183]
	global_store_dwordx4 v152, v[180:183], s[64:65] offset:2048
	v_pk_add_f32 v[124:125], v[124:125], v[140:141]
	v_pk_add_f32 v[126:127], v[126:127], v[142:143]
	v_pk_fma_f32 v[184:185], v[124:125], v[64:65], v[184:185]
	v_pk_fma_f32 v[186:187], v[126:127], v[66:67], v[186:187]
	global_store_dwordx4 v152, v[184:187], s[64:65] offset:3072
	v_add_u32_e32 v152, 0x1000, v152
	v_pk_mul_f32 v[242:243], v[172:173], v[172:173]
	v_pk_mul_f32 v[244:245], v[176:177], v[176:177]
	v_pk_mul_f32 v[246:247], v[174:175], v[174:175]
	v_pk_mul_f32 v[248:249], v[178:179], v[178:179]
	v_add_f32_e32 v204, v245, v244
	v_add_f32_e32 v205, v243, v242
	v_add_f32_e32 v204, v248, v204
	v_add_f32_e32 v205, v246, v205
	v_add_f32_e32 v204, v249, v204
	v_add_f32_e32 v205, v247, v205
	v_pk_mul_f32 v[242:243], v[180:181], v[180:181]
	v_pk_mul_f32 v[244:245], v[184:185], v[184:185]
	v_pk_mul_f32 v[246:247], v[182:183], v[182:183]
	v_pk_mul_f32 v[248:249], v[186:187], v[186:187]
	v_add_f32_e32 v206, v243, v242
	v_add_f32_e32 v207, v245, v244
	v_add_f32_e32 v206, v246, v206
	v_add_f32_e32 v207, v248, v207
	v_add_f32_e32 v206, v247, v206
	v_add_f32_e32 v207, v249, v207
	v_add_f32_e32 v204, v205, v204
	v_add_f32_e32 v204, v204, v206
	v_add_f32_e32 v204, v204, v207
	ds_swizzle_b32 v205, v204 offset:swizzle(SWAP,1)
	s_waitcnt lgkmcnt(0)
	v_add_f32_e32 v204, v204, v205
	ds_swizzle_b32 v205, v204 offset:swizzle(SWAP,2)
	s_waitcnt lgkmcnt(0)
	v_add_f32_e32 v204, v204, v205
	ds_swizzle_b32 v205, v204 offset:swizzle(SWAP,4)
	s_waitcnt lgkmcnt(0)
	v_add_f32_e32 v204, v204, v205
	ds_swizzle_b32 v205, v204 offset:swizzle(SWAP,8)
	s_waitcnt lgkmcnt(0)
	v_add_f32_e32 v204, v204, v205
	ds_swizzle_b32 v205, v204 offset:swizzle(SWAP,16)
	s_waitcnt lgkmcnt(0)
	v_add_f32_e32 v204, v204, v205
	v_mov_b32_e32 v205, v204
	s_nop 1
	v_permlane32_swap_b32_e32 v204, v205
	v_add_f32_e32 v204, v204, v205
	v_mov_b32_e32 v205, 0x358637bd
	v_fmamk_f32 v204, v204, 0x3a800000, v205
	v_rsq_f32_e32 v204, v204
	s_nop 0
	v_pk_mul_f32 v[172:173], v[172:173], v[204:205] op_sel_hi:[1,0]
	v_pk_mul_f32 v[174:175], v[174:175], v[204:205] op_sel_hi:[1,0]
	v_pk_mul_f32 v[172:173], v[188:189], v[172:173]
	v_pk_mul_f32 v[174:175], v[190:191], v[174:175]
	v_pk_fma_f32 v[172:173], v[34:35], v[172:173], v[224:225]
	v_pk_fma_f32 v[174:175], v[36:37], v[174:175], v[226:227]
	v_cvt_pk_bf16_f32 v172, v172, v173
	v_cvt_pk_bf16_f32 v173, v174, v175
	global_store_dwordx2 v146, v[172:173], s[66:67]
	v_pk_mul_f32 v[176:177], v[176:177], v[204:205] op_sel_hi:[1,0]
	v_pk_mul_f32 v[178:179], v[178:179], v[204:205] op_sel_hi:[1,0]
	v_pk_mul_f32 v[176:177], v[192:193], v[176:177]
	v_pk_mul_f32 v[178:179], v[194:195], v[178:179]
	v_pk_fma_f32 v[176:177], v[38:39], v[176:177], v[228:229]
	v_pk_fma_f32 v[178:179], v[40:41], v[178:179], v[230:231]
	v_cvt_pk_bf16_f32 v176, v176, v177
	v_cvt_pk_bf16_f32 v177, v178, v179
	global_store_dwordx2 v146, v[176:177], s[66:67] offset:512
	v_pk_mul_f32 v[180:181], v[180:181], v[204:205] op_sel_hi:[1,0]
	v_pk_mul_f32 v[182:183], v[182:183], v[204:205] op_sel_hi:[1,0]
	v_pk_mul_f32 v[180:181], v[196:197], v[180:181]
	v_pk_mul_f32 v[182:183], v[198:199], v[182:183]
	v_pk_fma_f32 v[180:181], v[42:43], v[180:181], v[232:233]
	v_pk_fma_f32 v[182:183], v[44:45], v[182:183], v[234:235]
	v_cvt_pk_bf16_f32 v180, v180, v181
	v_cvt_pk_bf16_f32 v181, v182, v183
	global_store_dwordx2 v146, v[180:181], s[66:67] offset:1024
	v_pk_mul_f32 v[184:185], v[184:185], v[204:205] op_sel_hi:[1,0]
	v_pk_mul_f32 v[186:187], v[186:187], v[204:205] op_sel_hi:[1,0]
	v_pk_mul_f32 v[184:185], v[200:201], v[184:185]
	v_pk_mul_f32 v[186:187], v[202:203], v[186:187]
	v_pk_fma_f32 v[184:185], v[46:47], v[184:185], v[236:237]
	v_pk_fma_f32 v[186:187], v[48:49], v[186:187], v[238:239]
	v_cvt_pk_bf16_f32 v184, v184, v185
	v_cvt_pk_bf16_f32 v185, v186, v187
	global_store_dwordx2 v146, v[184:185], s[66:67] offset:1536
	v_add_u32_e32 v146, 0x800, v146
	s_branch .Lnorm_P1_end

; __device__ __forceinline__ unsigned xb_ld(unsigned* p)              { return __hip_atomic_load(p, __ATOMIC_RELAXED, __HIP_MEMORY_SCOPE_AGENT); }
; __device__ __forceinline__ unsigned xb_add(unsigned* p, unsigned v) { return __hip_atomic_fetch_add(p, v, __ATOMIC_RELAXED, __HIP_MEMORY_SCOPE_AGENT); }
; #define XB_SPIN(cond, bar) do { unsigned _sp = 0; while (cond) { __builtin_amdgcn_s_sleep(1); \
;     if ((++_sp & 255u) == 0u) { if (xb_ld(&(bar)[XB_TMO])) break; if (_sp > XB_SPIN_CAP) { atomicAdd(&(bar)[XB_TMO], 1u); break; } } } } while (0)
; __device__ __forceinline__ void xcd_barrier(const XcdBarrier& b) {
;     ...
;         const unsigned old = xb_add(&bar[XB_XSUB(b.x)], 1u);
;         const unsigned gen = old / nloc;
;         if (old + 1u == (gen + 1u) * nloc) {
;             __builtin_amdgcn_fence(__ATOMIC_RELEASE, "agent");
;             asm volatile("s_waitcnt vmcnt(0)" ::: "memory");
;             const unsigned og = xb_add(&bar[XB_TOP], 1u);
;             const unsigned tg = og / nx;
;             if (og + 1u == (tg + 1u) * nx) xb_add(&bar[XB_TOPGEN], 1u);
;             else XB_SPIN(xb_ld(&bar[XB_TOPGEN]) == tg, bar);
;             __builtin_amdgcn_fence(__ATOMIC_ACQUIRE, "agent");
;             xb_add(&bar[XB_XGEN(b.x)], 1u);
;             asm volatile("s_waitcnt vmcnt(0)" ::: "memory");
.LBB0_1178:
	s_cmp_lg_u32 s63, 2
	s_cbranch_scc1 .Lfz_sig_skip
	v_readlane_b32 s98, v255, 45
	s_cmp_gt_u32 s98, 2
	s_cbranch_scc1 .Lfz_sig_skip
	s_waitcnt vmcnt(0)
	s_barrier
	s_barrier
	v_cmp_eq_u32_e32 vcc, 0x100, v253
	s_and_saveexec_b64 s[100:101], vcc
	s_cbranch_execz .Lfz_sig_done
	v_readlane_b32 s98, v255, 27
	s_nop 0
	v_mov_b32_e32 v2, s98
	ds_read_b32 v3, v2
	v_readlane_b32 s98, v255, 35
	v_readlane_b32 s99, v255, 36
	v_readlane_b32 s97, v254, 63
	s_nop 0
	s_sub_u32 s97, s97, s98
	s_sub_u32 s97, s97, 0x1200
	s_lshr_b32 s97, s97, 4
	s_add_u32 s98, s98, s97
	s_addc_u32 s99, s99, 0
	v_mov_b32_e32 v2, 1
	s_nop 1
	global_atomic_add v2, v0, v2, s[98:99] offset:-512 sc0
	v_readlane_b32 s97, v255, 45
	s_nop 0
	s_add_i32 s97, s97, 1
	s_waitcnt vmcnt(0) lgkmcnt(0)
	v_mul_lo_u32 v3, v3, s97
	v_add_u32_e32 v2, 1, v2
	v_cmp_eq_u32_e32 vcc, v2, v3
	s_cbranch_vccz .Lfz_sig_done
	buffer_wbl2 sc1
	s_waitcnt vmcnt(0)
	v_readlane_b32 s98, v255, 35
	v_readlane_b32 s99, v255, 36
	v_mov_b32_e32 v2, 1
	s_nop 4
	global_atomic_add v0, v2, s[98:99] offset:-256
	s_waitcnt vmcnt(0)
.Lfz_sig_done:
	s_or_b64 exec, exec, s[100:101]

; __device__ __forceinline__ int obid() { int b = blockIdx.x; asm volatile("" : "+s"(b)); return b; }
; __device__ __forceinline__ int otid() { int t = threadIdx.x; asm volatile("" : "+v"(t)); return t; }
; #define PN_LOAD(dst, rw) do { const float* s_ = (rw) < NLAT ? hlat + (size_t)(rw) * 1024 : hctx + (size_t)((rw) - NLAT) * 1024; \
;         _Pragma("unroll") for (int i = 0; i < 4; ++i) dst[i] = *(const float4*)(s_ + i * 256 + lane * 4); } while (0)
; __device__ __forceinline__ void p_norm(const float* hlat, const float* hctx, const float* g, const float* modl, int sh_off, int sc_off, bf16_t* A, int M,
;                                        const float* part, const float* cgate, float* hcout) {
;     const int tid = otid(), lane = tid & 63, wave = tid >> 6;
;     const int stride = gridDim.x * 8;
;     int row = obid() * 8 + wave;
;     float4 v[4], nv[4];
;     ...
;     if (row < M) PN_LOAD(v, row);
;     while (row < M) {
;         const int nrow = row + stride;
;         if (nrow < M) PN_LOAD(nv, nrow);
;         const int r = row < NLAT ? (row >> 11) : 16;
;         float ss = 0.f;
; #pragma unroll
;         for (int i = 0; i < 4; ++i) {
;             if (part != nullptr && row >= NLAT) {
;                 const size_t po = (size_t)(row - NLAT) * 1024 + i * 256 + lane * 4;
;                 const float4 p0 = *(const float4*)(part + po), p1 = *(const float4*)(part + (size_t)4096 * 1024 + po), cg = *(const float4*)(cgate + i * 256 + lane * 4);
;                 v[i].x += cg.x * (p0.x + p1.x); v[i].y += cg.y * (p0.y + p1.y); v[i].z += cg.z * (p0.z + p1.z); v[i].w += cg.w * (p0.w + p1.w);
;                 *(float4*)(hcout + po) = v[i];
;             }
;             ss += v[i].x * v[i].x + v[i].y * v[i].y + v[i].z * v[i].z + v[i].w * v[i].w; }
;         ss = wave_sum(ss);
;         const float rstd = rsqrtf(ss * (1.0f / 1024.0f) + EPS);
;         const float* mr = modl + (size_t)r * 6144;
.LBB0_1204:
	s_barrier
	v_readlane_b32 s100, v255, 45
	s_cmp_gt_u32 s100, 2
	s_cbranch_scc1 .Lfz_skip
	s_cmp_lt_u32 s63, 0x80
	s_cbranch_scc1 .Lfz_skip
	s_waitcnt vmcnt(0) lgkmcnt(0)
	s_and_saveexec_b64 s[98:99], s[12:13]
	s_cbranch_execz .Lfz_w_done
	v_readlane_b32 s97, v255, 28
	s_nop 0
	v_mov_b32_e32 v1, s97
	ds_read_b32 v1, v1
	s_add_i32 s101, s100, 1
	s_waitcnt lgkmcnt(0)
	v_readfirstlane_b32 s97, v1
	s_mul_i32 s101, s101, s97
.Lfz_spin:
	global_load_dword v1, v0, s[52:53] offset:-256 sc1
	s_waitcnt vmcnt(0)
	v_readfirstlane_b32 s97, v1
	s_cmp_ge_u32 s97, s101
	s_cbranch_scc1 .Lfz_w_ok
	s_sleep 2
	s_branch .Lfz_spin
.Lfz_w_ok:
	buffer_inv sc1
	s_waitcnt vmcnt(0)
.Lfz_w_done:
	s_or_b64 exec, exec, s[98:99]
	s_barrier
	s_add_i32 s100, s100, 1
	s_load_dwordx2 s[48:49], s[0:1], 0x30
	s_movk_i32 s101, 0xe8
	s_load_dwordx2 s[46:47], s[0:1], s101
	s_mul_i32 s101, s100, 0x66000
	s_add_u32 s50, s56, s101
	s_addc_u32 s51, s57, 0
	s_add_u32 s98, s50, 0x1000
	s_addc_u32 s99, s51, 0
	s_lshl_b32 s101, s100, 12
	v_and_b32_e32 v240, 63, v253
	v_lshlrev_b32_e32 v241, 4, v240
	s_waitcnt lgkmcnt(0)
	s_add_u32 s48, s48, s101
	s_addc_u32 s49, s49, 0
	s_mov_b32 s97, 0
.Lfz_pass:
	s_sub_i32 s101, s63, 0x80
	s_lshl_b32 s101, s101, 1
	s_add_i32 s101, s101, s97
	s_lshl_b32 s101, s101, 3
	v_lshrrev_b32_e32 v204, 6, v253
	v_add_u32_e32 v153, s101, v204
	v_lshrrev_b32_e32 v148, 7, v153
	v_lshlrev_b32_e32 v146, 4, v153
	v_lshl_add_u32 v144, v146, 12, v241
	v_lshlrev_b32_e32 v146, 11, v146
	v_lshl_add_u32 v146, v240, 3, v146
	v_mul_u32_u24_e32 v148, 0x6000, v148
	v_add_u32_e32 v148, v148, v241
	global_load_dwordx4 v[80:83], v144, s[46:47] nt
	global_load_dwordx4 v[84:87], v144, s[46:47] offset:1024 nt
	global_load_dwordx4 v[88:91], v144, s[46:47] offset:2048 nt
	global_load_dwordx4 v[92:95], v144, s[46:47] offset:3072 nt
	v_add_u32_e32 v144, 0x1000, v144
	global_load_dwordx4 v[34:37], v148, s[98:99]
	global_load_dwordx4 v[38:41], v148, s[98:99] offset:1024
	global_load_dwordx4 v[42:45], v148, s[98:99] offset:2048
	global_load_dwordx4 v[46:49], v148, s[98:99] offset:3072
	global_load_dwordx4 v[224:227], v148, s[50:51]
	global_load_dwordx4 v[228:231], v148, s[50:51] offset:1024
	global_load_dwordx4 v[232:235], v148, s[50:51] offset:2048
	global_load_dwordx4 v[236:239], v148, s[50:51] offset:3072
	global_load_dwordx4 v[188:191], v241, s[48:49]
	global_load_dwordx4 v[192:195], v241, s[48:49] offset:1024
	global_load_dwordx4 v[196:199], v241, s[48:49] offset:2048
	global_load_dwordx4 v[200:203], v241, s[48:49] offset:3072
	global_load_dwordx4 v[96:99], v144, s[46:47] nt
	global_load_dwordx4 v[100:103], v144, s[46:47] offset:1024 nt
	global_load_dwordx4 v[104:107], v144, s[46:47] offset:2048 nt
	global_load_dwordx4 v[108:111], v144, s[46:47] offset:3072 nt
	v_add_u32_e32 v144, 0x1000, v144
	global_load_dwordx4 v[112:115], v144, s[46:47] nt
	global_load_dwordx4 v[116:119], v144, s[46:47] offset:1024 nt
	global_load_dwordx4 v[120:123], v144, s[46:47] offset:2048 nt
	global_load_dwordx4 v[124:127], v144, s[46:47] offset:3072 nt
	v_add_u32_e32 v144, 0x1000, v144
	global_load_dwordx4 v[128:131], v144, s[46:47] nt
	global_load_dwordx4 v[132:135], v144, s[46:47] offset:1024 nt
	global_load_dwordx4 v[136:139], v144, s[46:47] offset:2048 nt
	global_load_dwordx4 v[140:143], v144, s[46:47] offset:3072 nt
	v_add_u32_e32 v144, 0x1000, v144
	global_load_dwordx4 v[156:159], v144, s[46:47] nt
	global_load_dwordx4 v[160:163], v144, s[46:47] offset:1024 nt
	global_load_dwordx4 v[164:167], v144, s[46:47] offset:2048 nt
	global_load_dwordx4 v[168:171], v144, s[46:47] offset:3072 nt
	v_add_u32_e32 v144, 0x1000, v144
	global_load_dwordx4 v[172:175], v144, s[46:47] nt
	global_load_dwordx4 v[176:179], v144, s[46:47] offset:1024 nt
	global_load_dwordx4 v[180:183], v144, s[46:47] offset:2048 nt
	global_load_dwordx4 v[184:187], v144, s[46:47] offset:3072 nt
	v_add_u32_e32 v144, 0x1000, v144
	s_waitcnt vmcnt(32)
	v_pk_mul_f32 v[242:243], v[80:81], v[80:81]
	v_pk_mul_f32 v[244:245], v[84:85], v[84:85]
	v_pk_mul_f32 v[246:247], v[82:83], v[82:83]
	v_pk_mul_f32 v[248:249], v[86:87], v[86:87]
	v_add_f32_e32 v204, v245, v244
	v_add_f32_e32 v205, v243, v242
	v_add_f32_e32 v204, v248, v204
	v_add_f32_e32 v205, v246, v205
	v_add_f32_e32 v204, v249, v204
	v_add_f32_e32 v205, v247, v205
	v_pk_mul_f32 v[242:243], v[88:89], v[88:89]
	v_pk_mul_f32 v[244:245], v[92:93], v[92:93]
	v_pk_mul_f32 v[246:247], v[90:91], v[90:91]
	v_pk_mul_f32 v[248:249], v[94:95], v[94:95]
	v_add_f32_e32 v206, v243, v242
	v_add_f32_e32 v207, v245, v244
	v_add_f32_e32 v206, v246, v206
	v_add_f32_e32 v207, v248, v207
	v_add_f32_e32 v206, v247, v206
	v_add_f32_e32 v207, v249, v207
	v_add_f32_e32 v204, v205, v204
	v_add_f32_e32 v204, v204, v206
	v_add_f32_e32 v204, v204, v207
	ds_swizzle_b32 v205, v204 offset:swizzle(SWAP,1)
	s_waitcnt lgkmcnt(0)
	v_add_f32_e32 v204, v204, v205
	ds_swizzle_b32 v205, v204 offset:swizzle(SWAP,2)
	s_waitcnt lgkmcnt(0)
	v_add_f32_e32 v204, v204, v205
	ds_swizzle_b32 v205, v204 offset:swizzle(SWAP,4)
	s_waitcnt lgkmcnt(0)
	v_add_f32_e32 v204, v204, v205
	ds_swizzle_b32 v205, v204 offset:swizzle(SWAP,8)
	s_waitcnt lgkmcnt(0)
	v_add_f32_e32 v204, v204, v205
	ds_swizzle_b32 v205, v204 offset:swizzle(SWAP,16)
	s_waitcnt lgkmcnt(0)
	v_add_f32_e32 v204, v204, v205
	v_mov_b32_e32 v205, v204
	s_nop 1
	v_permlane32_swap_b32_e32 v204, v205
	v_add_f32_e32 v204, v204, v205
	v_mov_b32_e32 v205, 0x358637bd
	v_fmamk_f32 v204, v204, 0x3a800000, v205
	v_rsq_f32_e32 v204, v204
	s_nop 0
	s_waitcnt vmcnt(20)
; __device__ __forceinline__ unsigned pk2(float lo, float hi) { const g_f32x2 f = {lo, hi}; return __builtin_bit_cast(unsigned, __builtin_convertvector(f, g_bf16x2)); }
; __device__ __forceinline__ void p_norm(const float* hlat, const float* hctx, const float* g, const float* modl, int sh_off, int sc_off, bf16_t* A, int M,
;                                        const float* part, const float* cgate, float* hcout) {
;     ...
;         float ss = 0.f;
; #pragma unroll
;         for (int i = 0; i < 4; ++i) {
;             if (part != nullptr && row >= NLAT) {
;                 const size_t po = (size_t)(row - NLAT) * 1024 + i * 256 + lane * 4;
;                 const float4 p0 = *(const float4*)(part + po), p1 = *(const float4*)(part + (size_t)4096 * 1024 + po), cg = *(const float4*)(cgate + i * 256 + lane * 4);
;                 v[i].x += cg.x * (p0.x + p1.x); v[i].y += cg.y * (p0.y + p1.y); v[i].z += cg.z * (p0.z + p1.z); v[i].w += cg.w * (p0.w + p1.w);
;                 *(float4*)(hcout + po) = v[i];
;             }
;             ss += v[i].x * v[i].x + v[i].y * v[i].y + v[i].z * v[i].z + v[i].w * v[i].w; }
;         ss = wave_sum(ss);
;         const float rstd = rsqrtf(ss * (1.0f / 1024.0f) + EPS);
;         const float* mr = modl + (size_t)r * 6144;
; #pragma unroll
;         for (int i = 0; i < 4; ++i) {
;             const int k = i * 256 + lane * 4;
;             const float4 gg = *(const float4*)(g + k), scv = *(const float4*)(mr + sc_off + k), shv = *(const float4*)(mr + sh_off + k);
;             const float o0 = v[i].x * rstd * gg.x * (1.0f + scv.x) + shv.x, o1 = v[i].y * rstd * gg.y * (1.0f + scv.y) + shv.y;
;             const float o2 = v[i].z * rstd * gg.z * (1.0f + scv.z) + shv.z, o3 = v[i].w * rstd * gg.w * (1.0f + scv.w) + shv.w;
;             uint2 w; w.x = pk2(o0, o1); w.y = pk2(o2, o3);
;             *(uint2*)(A + (size_t)row * 1024 + k) = w;
;         }
; #pragma unroll
;         for (int i = 0; i < 4; ++i) v[i] = nv[i];
;         row = nrow;
;     }
	v_pk_add_f32 v[34:35], v[34:35], 1.0 op_sel_hi:[1,0]
	v_pk_add_f32 v[36:37], v[36:37], 1.0 op_sel_hi:[1,0]
	v_pk_add_f32 v[38:39], v[38:39], 1.0 op_sel_hi:[1,0]
	v_pk_add_f32 v[40:41], v[40:41], 1.0 op_sel_hi:[1,0]
	v_pk_add_f32 v[42:43], v[42:43], 1.0 op_sel_hi:[1,0]
	v_pk_add_f32 v[44:45], v[44:45], 1.0 op_sel_hi:[1,0]
	v_pk_add_f32 v[46:47], v[46:47], 1.0 op_sel_hi:[1,0]
	v_pk_add_f32 v[48:49], v[48:49], 1.0 op_sel_hi:[1,0]
	v_pk_mul_f32 v[80:81], v[80:81], v[204:205] op_sel_hi:[1,0]
	v_pk_mul_f32 v[82:83], v[82:83], v[204:205] op_sel_hi:[1,0]
	v_pk_mul_f32 v[80:81], v[188:189], v[80:81]
	v_pk_mul_f32 v[82:83], v[190:191], v[82:83]
	v_pk_fma_f32 v[80:81], v[34:35], v[80:81], v[224:225]
	v_pk_fma_f32 v[82:83], v[36:37], v[82:83], v[226:227]
	v_cvt_pk_bf16_f32 v80, v80, v81
	v_cvt_pk_bf16_f32 v81, v82, v83
	global_store_dwordx2 v146, v[80:81], s[66:67]
	v_pk_mul_f32 v[84:85], v[84:85], v[204:205] op_sel_hi:[1,0]
	v_pk_mul_f32 v[86:87], v[86:87], v[204:205] op_sel_hi:[1,0]
	v_pk_mul_f32 v[84:85], v[192:193], v[84:85]
	v_pk_mul_f32 v[86:87], v[194:195], v[86:87]
	v_pk_fma_f32 v[84:85], v[38:39], v[84:85], v[228:229]
	v_pk_fma_f32 v[86:87], v[40:41], v[86:87], v[230:231]
	v_cvt_pk_bf16_f32 v84, v84, v85
	v_cvt_pk_bf16_f32 v85, v86, v87
	global_store_dwordx2 v146, v[84:85], s[66:67] offset:512
	v_pk_mul_f32 v[88:89], v[88:89], v[204:205] op_sel_hi:[1,0]
	v_pk_mul_f32 v[90:91], v[90:91], v[204:205] op_sel_hi:[1,0]
	v_pk_mul_f32 v[88:89], v[196:197], v[88:89]
	v_pk_mul_f32 v[90:91], v[198:199], v[90:91]
	v_pk_fma_f32 v[88:89], v[42:43], v[88:89], v[232:233]
	v_pk_fma_f32 v[90:91], v[44:45], v[90:91], v[234:235]
	v_cvt_pk_bf16_f32 v88, v88, v89
	v_cvt_pk_bf16_f32 v89, v90, v91
	global_store_dwordx2 v146, v[88:89], s[66:67] offset:1024
	v_pk_mul_f32 v[92:93], v[92:93], v[204:205] op_sel_hi:[1,0]
	v_pk_mul_f32 v[94:95], v[94:95], v[204:205] op_sel_hi:[1,0]
	v_pk_mul_f32 v[92:93], v[200:201], v[92:93]
	v_pk_mul_f32 v[94:95], v[202:203], v[94:95]
	v_pk_fma_f32 v[92:93], v[46:47], v[92:93], v[236:237]
	v_pk_fma_f32 v[94:95], v[48:49], v[94:95], v[238:239]
	v_cvt_pk_bf16_f32 v92, v92, v93
	v_cvt_pk_bf16_f32 v93, v94, v95
	global_store_dwordx2 v146, v[92:93], s[66:67] offset:1536
	v_add_u32_e32 v146, 0x800, v146
	global_load_dwordx4 v[80:83], v144, s[46:47] nt
	global_load_dwordx4 v[84:87], v144, s[46:47] offset:1024 nt
	global_load_dwordx4 v[88:91], v144, s[46:47] offset:2048 nt
	global_load_dwordx4 v[92:95], v144, s[46:47] offset:3072 nt
	v_add_u32_e32 v144, 0x1000, v144
	s_waitcnt vmcnt(24)
	v_pk_mul_f32 v[242:243], v[96:97], v[96:97]
	v_pk_mul_f32 v[244:245], v[100:101], v[100:101]
	v_pk_mul_f32 v[246:247], v[98:99], v[98:99]
	v_pk_mul_f32 v[248:249], v[102:103], v[102:103]
	v_add_f32_e32 v204, v245, v244
	v_add_f32_e32 v205, v243, v242
	v_add_f32_e32 v204, v248, v204
	v_add_f32_e32 v205, v246, v205
	v_add_f32_e32 v204, v249, v204
	v_add_f32_e32 v205, v247, v205
	v_pk_mul_f32 v[242:243], v[104:105], v[104:105]
	v_pk_mul_f32 v[244:245], v[108:109], v[108:109]
	v_pk_mul_f32 v[246:247], v[106:107], v[106:107]
	v_pk_mul_f32 v[248:249], v[110:111], v[110:111]
	v_add_f32_e32 v206, v243, v242
	v_add_f32_e32 v207, v245, v244
	v_add_f32_e32 v206, v246, v206
	v_add_f32_e32 v207, v248, v207
	v_add_f32_e32 v206, v247, v206
	v_add_f32_e32 v207, v249, v207
	v_add_f32_e32 v204, v205, v204
	v_add_f32_e32 v204, v204, v206
	v_add_f32_e32 v204, v204, v207
	ds_swizzle_b32 v205, v204 offset:swizzle(SWAP,1)
	s_waitcnt lgkmcnt(0)
	v_add_f32_e32 v204, v204, v205
	ds_swizzle_b32 v205, v204 offset:swizzle(SWAP,2)
	s_waitcnt lgkmcnt(0)
	v_add_f32_e32 v204, v204, v205
	ds_swizzle_b32 v205, v204 offset:swizzle(SWAP,4)
	s_waitcnt lgkmcnt(0)
	v_add_f32_e32 v204, v204, v205
	ds_swizzle_b32 v205, v204 offset:swizzle(SWAP,8)
	s_waitcnt lgkmcnt(0)
	v_add_f32_e32 v204, v204, v205
	ds_swizzle_b32 v205, v204 offset:swizzle(SWAP,16)
	s_waitcnt lgkmcnt(0)
	v_add_f32_e32 v204, v204, v205
	v_mov_b32_e32 v205, v204
	s_nop 1
	v_permlane32_swap_b32_e32 v204, v205
	v_add_f32_e32 v204, v204, v205
	v_mov_b32_e32 v205, 0x358637bd
	v_fmamk_f32 v204, v204, 0x3a800000, v205
	v_rsq_f32_e32 v204, v204
	s_nop 0
	v_pk_mul_f32 v[96:97], v[96:97], v[204:205] op_sel_hi:[1,0]
	v_pk_mul_f32 v[98:99], v[98:99], v[204:205] op_sel_hi:[1,0]
	v_pk_mul_f32 v[96:97], v[188:189], v[96:97]
	v_pk_mul_f32 v[98:99], v[190:191], v[98:99]
	v_pk_fma_f32 v[96:97], v[34:35], v[96:97], v[224:225]
	v_pk_fma_f32 v[98:99], v[36:37], v[98:99], v[226:227]
	v_cvt_pk_bf16_f32 v96, v96, v97
	v_cvt_pk_bf16_f32 v97, v98, v99
	global_store_dwordx2 v146, v[96:97], s[66:67]
	v_pk_mul_f32 v[100:101], v[100:101], v[204:205] op_sel_hi:[1,0]
	v_pk_mul_f32 v[102:103], v[102:103], v[204:205] op_sel_hi:[1,0]
	v_pk_mul_f32 v[100:101], v[192:193], v[100:101]
	v_pk_mul_f32 v[102:103], v[194:195], v[102:103]
	v_pk_fma_f32 v[100:101], v[38:39], v[100:101], v[228:229]
	v_pk_fma_f32 v[102:103], v[40:41], v[102:103], v[230:231]
	v_cvt_pk_bf16_f32 v100, v100, v101
	v_cvt_pk_bf16_f32 v101, v102, v103
	global_store_dwordx2 v146, v[100:101], s[66:67] offset:512
	v_pk_mul_f32 v[104:105], v[104:105], v[204:205] op_sel_hi:[1,0]
	v_pk_mul_f32 v[106:107], v[106:107], v[204:205] op_sel_hi:[1,0]
	v_pk_mul_f32 v[104:105], v[196:197], v[104:105]
	v_pk_mul_f32 v[106:107], v[198:199], v[106:107]
	v_pk_fma_f32 v[104:105], v[42:43], v[104:105], v[232:233]
	v_pk_fma_f32 v[106:107], v[44:45], v[106:107], v[234:235]
	v_cvt_pk_bf16_f32 v104, v104, v105
	v_cvt_pk_bf16_f32 v105, v106, v107
	global_store_dwordx2 v146, v[104:105], s[66:67] offset:1024
	v_pk_mul_f32 v[108:109], v[108:109], v[204:205] op_sel_hi:[1,0]
	v_pk_mul_f32 v[110:111], v[110:111], v[204:205] op_sel_hi:[1,0]
	v_pk_mul_f32 v[108:109], v[200:201], v[108:109]
	v_pk_mul_f32 v[110:111], v[202:203], v[110:111]
	v_pk_fma_f32 v[108:109], v[46:47], v[108:109], v[236:237]
	v_pk_fma_f32 v[110:111], v[48:49], v[110:111], v[238:239]
	v_cvt_pk_bf16_f32 v108, v108, v109
	v_cvt_pk_bf16_f32 v109, v110, v111
	global_store_dwordx2 v146, v[108:109], s[66:67] offset:1536
	v_add_u32_e32 v146, 0x800, v146
	global_load_dwordx4 v[96:99], v144, s[46:47] nt
	global_load_dwordx4 v[100:103], v144, s[46:47] offset:1024 nt
	global_load_dwordx4 v[104:107], v144, s[46:47] offset:2048 nt
	global_load_dwordx4 v[108:111], v144, s[46:47] offset:3072 nt
	v_add_u32_e32 v144, 0x1000, v144
	s_waitcnt vmcnt(28)
; __device__ __forceinline__ unsigned pk2(float lo, float hi) { const g_f32x2 f = {lo, hi}; return __builtin_bit_cast(unsigned, __builtin_convertvector(f, g_bf16x2)); }
; __device__ __forceinline__ void p_norm(const float* hlat, const float* hctx, const float* g, const float* modl, int sh_off, int sc_off, bf16_t* A, int M,
;                                        const float* part, const float* cgate, float* hcout) {
;     ...
;         float ss = 0.f;
; #pragma unroll
;         for (int i = 0; i < 4; ++i) {
;             if (part != nullptr && row >= NLAT) {
;                 const size_t po = (size_t)(row - NLAT) * 1024 + i * 256 + lane * 4;
;                 const float4 p0 = *(const float4*)(part + po), p1 = *(const float4*)(part + (size_t)4096 * 1024 + po), cg = *(const float4*)(cgate + i * 256 + lane * 4);
;                 v[i].x += cg.x * (p0.x + p1.x); v[i].y += cg.y * (p0.y + p1.y); v[i].z += cg.z * (p0.z + p1.z); v[i].w += cg.w * (p0.w + p1.w);
;                 *(float4*)(hcout + po) = v[i];
;             }
;             ss += v[i].x * v[i].x + v[i].y * v[i].y + v[i].z * v[i].z + v[i].w * v[i].w; }
;         ss = wave_sum(ss);
;         const float rstd = rsqrtf(ss * (1.0f / 1024.0f) + EPS);
;         const float* mr = modl + (size_t)r * 6144;
; #pragma unroll
;         for (int i = 0; i < 4; ++i) {
;             const int k = i * 256 + lane * 4;
;             const float4 gg = *(const float4*)(g + k), scv = *(const float4*)(mr + sc_off + k), shv = *(const float4*)(mr + sh_off + k);
;             const float o0 = v[i].x * rstd * gg.x * (1.0f + scv.x) + shv.x, o1 = v[i].y * rstd * gg.y * (1.0f + scv.y) + shv.y;
;             const float o2 = v[i].z * rstd * gg.z * (1.0f + scv.z) + shv.z, o3 = v[i].w * rstd * gg.w * (1.0f + scv.w) + shv.w;
;             uint2 w; w.x = pk2(o0, o1); w.y = pk2(o2, o3);
;             *(uint2*)(A + (size_t)row * 1024 + k) = w;
;         }
; #pragma unroll
;         for (int i = 0; i < 4; ++i) v[i] = nv[i];
;         row = nrow;
;     }
	v_pk_mul_f32 v[242:243], v[112:113], v[112:113]
	v_pk_mul_f32 v[244:245], v[116:117], v[116:117]
	v_pk_mul_f32 v[246:247], v[114:115], v[114:115]
	v_pk_mul_f32 v[248:249], v[118:119], v[118:119]
	v_add_f32_e32 v204, v245, v244
	v_add_f32_e32 v205, v243, v242
	v_add_f32_e32 v204, v248, v204
	v_add_f32_e32 v205, v246, v205
	v_add_f32_e32 v204, v249, v204
	v_add_f32_e32 v205, v247, v205
	v_pk_mul_f32 v[242:243], v[120:121], v[120:121]
	v_pk_mul_f32 v[244:245], v[124:125], v[124:125]
	v_pk_mul_f32 v[246:247], v[122:123], v[122:123]
	v_pk_mul_f32 v[248:249], v[126:127], v[126:127]
	v_add_f32_e32 v206, v243, v242
	v_add_f32_e32 v207, v245, v244
	v_add_f32_e32 v206, v246, v206
	v_add_f32_e32 v207, v248, v207
	v_add_f32_e32 v206, v247, v206
	v_add_f32_e32 v207, v249, v207
	v_add_f32_e32 v204, v205, v204
	v_add_f32_e32 v204, v204, v206
	v_add_f32_e32 v204, v204, v207
	ds_swizzle_b32 v205, v204 offset:swizzle(SWAP,1)
	s_waitcnt lgkmcnt(0)
	v_add_f32_e32 v204, v204, v205
	ds_swizzle_b32 v205, v204 offset:swizzle(SWAP,2)
	s_waitcnt lgkmcnt(0)
	v_add_f32_e32 v204, v204, v205
	ds_swizzle_b32 v205, v204 offset:swizzle(SWAP,4)
	s_waitcnt lgkmcnt(0)
	v_add_f32_e32 v204, v204, v205
	ds_swizzle_b32 v205, v204 offset:swizzle(SWAP,8)
	s_waitcnt lgkmcnt(0)
	v_add_f32_e32 v204, v204, v205
	ds_swizzle_b32 v205, v204 offset:swizzle(SWAP,16)
	s_waitcnt lgkmcnt(0)
	v_add_f32_e32 v204, v204, v205
	v_mov_b32_e32 v205, v204
	s_nop 1
	v_permlane32_swap_b32_e32 v204, v205
	v_add_f32_e32 v204, v204, v205
	v_mov_b32_e32 v205, 0x358637bd
	v_fmamk_f32 v204, v204, 0x3a800000, v205
	v_rsq_f32_e32 v204, v204
	s_nop 0
	v_pk_mul_f32 v[112:113], v[112:113], v[204:205] op_sel_hi:[1,0]
	v_pk_mul_f32 v[114:115], v[114:115], v[204:205] op_sel_hi:[1,0]
	v_pk_mul_f32 v[112:113], v[188:189], v[112:113]
	v_pk_mul_f32 v[114:115], v[190:191], v[114:115]
	v_pk_fma_f32 v[112:113], v[34:35], v[112:113], v[224:225]
	v_pk_fma_f32 v[114:115], v[36:37], v[114:115], v[226:227]
	v_cvt_pk_bf16_f32 v112, v112, v113
	v_cvt_pk_bf16_f32 v113, v114, v115
	global_store_dwordx2 v146, v[112:113], s[66:67]
	v_pk_mul_f32 v[116:117], v[116:117], v[204:205] op_sel_hi:[1,0]
	v_pk_mul_f32 v[118:119], v[118:119], v[204:205] op_sel_hi:[1,0]
	v_pk_mul_f32 v[116:117], v[192:193], v[116:117]
	v_pk_mul_f32 v[118:119], v[194:195], v[118:119]
	v_pk_fma_f32 v[116:117], v[38:39], v[116:117], v[228:229]
	v_pk_fma_f32 v[118:119], v[40:41], v[118:119], v[230:231]
	v_cvt_pk_bf16_f32 v116, v116, v117
	v_cvt_pk_bf16_f32 v117, v118, v119
	global_store_dwordx2 v146, v[116:117], s[66:67] offset:512
	v_pk_mul_f32 v[120:121], v[120:121], v[204:205] op_sel_hi:[1,0]
	v_pk_mul_f32 v[122:123], v[122:123], v[204:205] op_sel_hi:[1,0]
	v_pk_mul_f32 v[120:121], v[196:197], v[120:121]
	v_pk_mul_f32 v[122:123], v[198:199], v[122:123]
	v_pk_fma_f32 v[120:121], v[42:43], v[120:121], v[232:233]
	v_pk_fma_f32 v[122:123], v[44:45], v[122:123], v[234:235]
	v_cvt_pk_bf16_f32 v120, v120, v121
	v_cvt_pk_bf16_f32 v121, v122, v123
	global_store_dwordx2 v146, v[120:121], s[66:67] offset:1024
	v_pk_mul_f32 v[124:125], v[124:125], v[204:205] op_sel_hi:[1,0]
	v_pk_mul_f32 v[126:127], v[126:127], v[204:205] op_sel_hi:[1,0]
	v_pk_mul_f32 v[124:125], v[200:201], v[124:125]
	v_pk_mul_f32 v[126:127], v[202:203], v[126:127]
	v_pk_fma_f32 v[124:125], v[46:47], v[124:125], v[236:237]
	v_pk_fma_f32 v[126:127], v[48:49], v[126:127], v[238:239]
	v_cvt_pk_bf16_f32 v124, v124, v125
	v_cvt_pk_bf16_f32 v125, v126, v127
	global_store_dwordx2 v146, v[124:125], s[66:67] offset:1536
	v_add_u32_e32 v146, 0x800, v146
	global_load_dwordx4 v[112:115], v144, s[46:47] nt
	global_load_dwordx4 v[116:119], v144, s[46:47] offset:1024 nt
	global_load_dwordx4 v[120:123], v144, s[46:47] offset:2048 nt
	global_load_dwordx4 v[124:127], v144, s[46:47] offset:3072 nt
	v_add_u32_e32 v144, 0x1000, v144
	s_waitcnt vmcnt(32)
	v_pk_mul_f32 v[242:243], v[128:129], v[128:129]
	v_pk_mul_f32 v[244:245], v[132:133], v[132:133]
	v_pk_mul_f32 v[246:247], v[130:131], v[130:131]
	v_pk_mul_f32 v[248:249], v[134:135], v[134:135]
	v_add_f32_e32 v204, v245, v244
	v_add_f32_e32 v205, v243, v242
	v_add_f32_e32 v204, v248, v204
	v_add_f32_e32 v205, v246, v205
	v_add_f32_e32 v204, v249, v204
	v_add_f32_e32 v205, v247, v205
	v_pk_mul_f32 v[242:243], v[136:137], v[136:137]
	v_pk_mul_f32 v[244:245], v[140:141], v[140:141]
	v_pk_mul_f32 v[246:247], v[138:139], v[138:139]
	v_pk_mul_f32 v[248:249], v[142:143], v[142:143]
	v_add_f32_e32 v206, v243, v242
	v_add_f32_e32 v207, v245, v244
	v_add_f32_e32 v206, v246, v206
	v_add_f32_e32 v207, v248, v207
	v_add_f32_e32 v206, v247, v206
	v_add_f32_e32 v207, v249, v207
	v_add_f32_e32 v204, v205, v204
	v_add_f32_e32 v204, v204, v206
	v_add_f32_e32 v204, v204, v207
	ds_swizzle_b32 v205, v204 offset:swizzle(SWAP,1)
	s_waitcnt lgkmcnt(0)
	v_add_f32_e32 v204, v204, v205
	ds_swizzle_b32 v205, v204 offset:swizzle(SWAP,2)
	s_waitcnt lgkmcnt(0)
	v_add_f32_e32 v204, v204, v205
	ds_swizzle_b32 v205, v204 offset:swizzle(SWAP,4)
	s_waitcnt lgkmcnt(0)
	v_add_f32_e32 v204, v204, v205
	ds_swizzle_b32 v205, v204 offset:swizzle(SWAP,8)
	s_waitcnt lgkmcnt(0)
	v_add_f32_e32 v204, v204, v205
	ds_swizzle_b32 v205, v204 offset:swizzle(SWAP,16)
	s_waitcnt lgkmcnt(0)
; __device__ __forceinline__ unsigned pk2(float lo, float hi) { const g_f32x2 f = {lo, hi}; return __builtin_bit_cast(unsigned, __builtin_convertvector(f, g_bf16x2)); }
; __device__ __forceinline__ void p_norm(const float* hlat, const float* hctx, const float* g, const float* modl, int sh_off, int sc_off, bf16_t* A, int M,
;                                        const float* part, const float* cgate, float* hcout) {
;     ...
;         float ss = 0.f;
; #pragma unroll
;         for (int i = 0; i < 4; ++i) {
;             if (part != nullptr && row >= NLAT) {
;                 const size_t po = (size_t)(row - NLAT) * 1024 + i * 256 + lane * 4;
;                 const float4 p0 = *(const float4*)(part + po), p1 = *(const float4*)(part + (size_t)4096 * 1024 + po), cg = *(const float4*)(cgate + i * 256 + lane * 4);
;                 v[i].x += cg.x * (p0.x + p1.x); v[i].y += cg.y * (p0.y + p1.y); v[i].z += cg.z * (p0.z + p1.z); v[i].w += cg.w * (p0.w + p1.w);
;                 *(float4*)(hcout + po) = v[i];
;             }
;             ss += v[i].x * v[i].x + v[i].y * v[i].y + v[i].z * v[i].z + v[i].w * v[i].w; }
;         ss = wave_sum(ss);
;         const float rstd = rsqrtf(ss * (1.0f / 1024.0f) + EPS);
;         const float* mr = modl + (size_t)r * 6144;
; #pragma unroll
;         for (int i = 0; i < 4; ++i) {
;             const int k = i * 256 + lane * 4;
;             const float4 gg = *(const float4*)(g + k), scv = *(const float4*)(mr + sc_off + k), shv = *(const float4*)(mr + sh_off + k);
;             const float o0 = v[i].x * rstd * gg.x * (1.0f + scv.x) + shv.x, o1 = v[i].y * rstd * gg.y * (1.0f + scv.y) + shv.y;
;             const float o2 = v[i].z * rstd * gg.z * (1.0f + scv.z) + shv.z, o3 = v[i].w * rstd * gg.w * (1.0f + scv.w) + shv.w;
;             uint2 w; w.x = pk2(o0, o1); w.y = pk2(o2, o3);
;             *(uint2*)(A + (size_t)row * 1024 + k) = w;
;         }
; #pragma unroll
;         for (int i = 0; i < 4; ++i) v[i] = nv[i];
;         row = nrow;
;     }
	v_add_f32_e32 v204, v204, v205
	v_mov_b32_e32 v205, v204
	s_nop 1
	v_permlane32_swap_b32_e32 v204, v205
	v_add_f32_e32 v204, v204, v205
	v_mov_b32_e32 v205, 0x358637bd
	v_fmamk_f32 v204, v204, 0x3a800000, v205
	v_rsq_f32_e32 v204, v204
	s_nop 0
	v_pk_mul_f32 v[128:129], v[128:129], v[204:205] op_sel_hi:[1,0]
	v_pk_mul_f32 v[130:131], v[130:131], v[204:205] op_sel_hi:[1,0]
	v_pk_mul_f32 v[128:129], v[188:189], v[128:129]
	v_pk_mul_f32 v[130:131], v[190:191], v[130:131]
	v_pk_fma_f32 v[128:129], v[34:35], v[128:129], v[224:225]
	v_pk_fma_f32 v[130:131], v[36:37], v[130:131], v[226:227]
	v_cvt_pk_bf16_f32 v128, v128, v129
	v_cvt_pk_bf16_f32 v129, v130, v131
	global_store_dwordx2 v146, v[128:129], s[66:67]
	v_pk_mul_f32 v[132:133], v[132:133], v[204:205] op_sel_hi:[1,0]
	v_pk_mul_f32 v[134:135], v[134:135], v[204:205] op_sel_hi:[1,0]
	v_pk_mul_f32 v[132:133], v[192:193], v[132:133]
	v_pk_mul_f32 v[134:135], v[194:195], v[134:135]
	v_pk_fma_f32 v[132:133], v[38:39], v[132:133], v[228:229]
	v_pk_fma_f32 v[134:135], v[40:41], v[134:135], v[230:231]
	v_cvt_pk_bf16_f32 v132, v132, v133
	v_cvt_pk_bf16_f32 v133, v134, v135
	global_store_dwordx2 v146, v[132:133], s[66:67] offset:512
	v_pk_mul_f32 v[136:137], v[136:137], v[204:205] op_sel_hi:[1,0]
	v_pk_mul_f32 v[138:139], v[138:139], v[204:205] op_sel_hi:[1,0]
	v_pk_mul_f32 v[136:137], v[196:197], v[136:137]
	v_pk_mul_f32 v[138:139], v[198:199], v[138:139]
	v_pk_fma_f32 v[136:137], v[42:43], v[136:137], v[232:233]
	v_pk_fma_f32 v[138:139], v[44:45], v[138:139], v[234:235]
	v_cvt_pk_bf16_f32 v136, v136, v137
	v_cvt_pk_bf16_f32 v137, v138, v139
	global_store_dwordx2 v146, v[136:137], s[66:67] offset:1024
	v_pk_mul_f32 v[140:141], v[140:141], v[204:205] op_sel_hi:[1,0]
	v_pk_mul_f32 v[142:143], v[142:143], v[204:205] op_sel_hi:[1,0]
	v_pk_mul_f32 v[140:141], v[200:201], v[140:141]
	v_pk_mul_f32 v[142:143], v[202:203], v[142:143]
	v_pk_fma_f32 v[140:141], v[46:47], v[140:141], v[236:237]
	v_pk_fma_f32 v[142:143], v[48:49], v[142:143], v[238:239]
	v_cvt_pk_bf16_f32 v140, v140, v141
	v_cvt_pk_bf16_f32 v141, v142, v143
	global_store_dwordx2 v146, v[140:141], s[66:67] offset:1536
	v_add_u32_e32 v146, 0x800, v146
	global_load_dwordx4 v[128:131], v144, s[46:47] nt
	global_load_dwordx4 v[132:135], v144, s[46:47] offset:1024 nt
	global_load_dwordx4 v[136:139], v144, s[46:47] offset:2048 nt
	global_load_dwordx4 v[140:143], v144, s[46:47] offset:3072 nt
	v_add_u32_e32 v144, 0x1000, v144
	s_waitcnt vmcnt(36)
	v_pk_mul_f32 v[242:243], v[156:157], v[156:157]
	v_pk_mul_f32 v[244:245], v[160:161], v[160:161]
	v_pk_mul_f32 v[246:247], v[158:159], v[158:159]
	v_pk_mul_f32 v[248:249], v[162:163], v[162:163]
	v_add_f32_e32 v204, v245, v244
	v_add_f32_e32 v205, v243, v242
	v_add_f32_e32 v204, v248, v204
	v_add_f32_e32 v205, v246, v205
	v_add_f32_e32 v204, v249, v204
	v_add_f32_e32 v205, v247, v205
	v_pk_mul_f32 v[242:243], v[164:165], v[164:165]
	v_pk_mul_f32 v[244:245], v[168:169], v[168:169]
	v_pk_mul_f32 v[246:247], v[166:167], v[166:167]
	v_pk_mul_f32 v[248:249], v[170:171], v[170:171]
	v_add_f32_e32 v206, v243, v242
	v_add_f32_e32 v207, v245, v244
	v_add_f32_e32 v206, v246, v206
	v_add_f32_e32 v207, v248, v207
	v_add_f32_e32 v206, v247, v206
	v_add_f32_e32 v207, v249, v207
	v_add_f32_e32 v204, v205, v204
	v_add_f32_e32 v204, v204, v206
	v_add_f32_e32 v204, v204, v207
	ds_swizzle_b32 v205, v204 offset:swizzle(SWAP,1)
	s_waitcnt lgkmcnt(0)
	v_add_f32_e32 v204, v204, v205
	ds_swizzle_b32 v205, v204 offset:swizzle(SWAP,2)
	s_waitcnt lgkmcnt(0)
	v_add_f32_e32 v204, v204, v205
	ds_swizzle_b32 v205, v204 offset:swizzle(SWAP,4)
	s_waitcnt lgkmcnt(0)
	v_add_f32_e32 v204, v204, v205
	ds_swizzle_b32 v205, v204 offset:swizzle(SWAP,8)
	s_waitcnt lgkmcnt(0)
	v_add_f32_e32 v204, v204, v205
	ds_swizzle_b32 v205, v204 offset:swizzle(SWAP,16)
	s_waitcnt lgkmcnt(0)
	v_add_f32_e32 v204, v204, v205
	v_mov_b32_e32 v205, v204
	s_nop 1
	v_permlane32_swap_b32_e32 v204, v205
	v_add_f32_e32 v204, v204, v205
	v_mov_b32_e32 v205, 0x358637bd
	v_fmamk_f32 v204, v204, 0x3a800000, v205
	v_rsq_f32_e32 v204, v204
	s_nop 0
	v_pk_mul_f32 v[156:157], v[156:157], v[204:205] op_sel_hi:[1,0]
	v_pk_mul_f32 v[158:159], v[158:159], v[204:205] op_sel_hi:[1,0]
	v_pk_mul_f32 v[156:157], v[188:189], v[156:157]
	v_pk_mul_f32 v[158:159], v[190:191], v[158:159]
	v_pk_fma_f32 v[156:157], v[34:35], v[156:157], v[224:225]
	v_pk_fma_f32 v[158:159], v[36:37], v[158:159], v[226:227]
	v_cvt_pk_bf16_f32 v156, v156, v157
	v_cvt_pk_bf16_f32 v157, v158, v159
	global_store_dwordx2 v146, v[156:157], s[66:67]
	v_pk_mul_f32 v[160:161], v[160:161], v[204:205] op_sel_hi:[1,0]
	v_pk_mul_f32 v[162:163], v[162:163], v[204:205] op_sel_hi:[1,0]
	v_pk_mul_f32 v[160:161], v[192:193], v[160:161]
	v_pk_mul_f32 v[162:163], v[194:195], v[162:163]
	v_pk_fma_f32 v[160:161], v[38:39], v[160:161], v[228:229]
	v_pk_fma_f32 v[162:163], v[40:41], v[162:163], v[230:231]
	v_cvt_pk_bf16_f32 v160, v160, v161
	v_cvt_pk_bf16_f32 v161, v162, v163
	global_store_dwordx2 v146, v[160:161], s[66:67] offset:512
	v_pk_mul_f32 v[164:165], v[164:165], v[204:205] op_sel_hi:[1,0]
	v_pk_mul_f32 v[166:167], v[166:167], v[204:205] op_sel_hi:[1,0]
	v_pk_mul_f32 v[164:165], v[196:197], v[164:165]
	v_pk_mul_f32 v[166:167], v[198:199], v[166:167]
	v_pk_fma_f32 v[164:165], v[42:43], v[164:165], v[232:233]
	v_pk_fma_f32 v[166:167], v[44:45], v[166:167], v[234:235]
	v_cvt_pk_bf16_f32 v164, v164, v165
	v_cvt_pk_bf16_f32 v165, v166, v167
	global_store_dwordx2 v146, v[164:165], s[66:67] offset:1024
	v_pk_mul_f32 v[168:169], v[168:169], v[204:205] op_sel_hi:[1,0]
	v_pk_mul_f32 v[170:171], v[170:171], v[204:205] op_sel_hi:[1,0]
	v_pk_mul_f32 v[168:169], v[200:201], v[168:169]
	v_pk_mul_f32 v[170:171], v[202:203], v[170:171]
	v_pk_fma_f32 v[168:169], v[46:47], v[168:169], v[236:237]
	v_pk_fma_f32 v[170:171], v[48:49], v[170:171], v[238:239]
	v_cvt_pk_bf16_f32 v168, v168, v169
	v_cvt_pk_bf16_f32 v169, v170, v171
	global_store_dwordx2 v146, v[168:169], s[66:67] offset:1536
	v_add_u32_e32 v146, 0x800, v146
	global_load_dwordx4 v[156:159], v144, s[46:47] nt
	global_load_dwordx4 v[160:163], v144, s[46:47] offset:1024 nt
	global_load_dwordx4 v[164:167], v144, s[46:47] offset:2048 nt
	global_load_dwordx4 v[168:171], v144, s[46:47] offset:3072 nt
	v_add_u32_e32 v144, 0x1000, v144
	s_waitcnt vmcnt(40)
; __device__ __forceinline__ unsigned pk2(float lo, float hi) { const g_f32x2 f = {lo, hi}; return __builtin_bit_cast(unsigned, __builtin_convertvector(f, g_bf16x2)); }
; __device__ __forceinline__ void p_norm(const float* hlat, const float* hctx, const float* g, const float* modl, int sh_off, int sc_off, bf16_t* A, int M,
;                                        const float* part, const float* cgate, float* hcout) {
;     ...
;         float ss = 0.f;
; #pragma unroll
;         for (int i = 0; i < 4; ++i) {
;             if (part != nullptr && row >= NLAT) {
;                 const size_t po = (size_t)(row - NLAT) * 1024 + i * 256 + lane * 4;
;                 const float4 p0 = *(const float4*)(part + po), p1 = *(const float4*)(part + (size_t)4096 * 1024 + po), cg = *(const float4*)(cgate + i * 256 + lane * 4);
;                 v[i].x += cg.x * (p0.x + p1.x); v[i].y += cg.y * (p0.y + p1.y); v[i].z += cg.z * (p0.z + p1.z); v[i].w += cg.w * (p0.w + p1.w);
;                 *(float4*)(hcout + po) = v[i];
;             }
;             ss += v[i].x * v[i].x + v[i].y * v[i].y + v[i].z * v[i].z + v[i].w * v[i].w; }
;         ss = wave_sum(ss);
;         const float rstd = rsqrtf(ss * (1.0f / 1024.0f) + EPS);
;         const float* mr = modl + (size_t)r * 6144;
; #pragma unroll
;         for (int i = 0; i < 4; ++i) {
;             const int k = i * 256 + lane * 4;
;             const float4 gg = *(const float4*)(g + k), scv = *(const float4*)(mr + sc_off + k), shv = *(const float4*)(mr + sh_off + k);
;             const float o0 = v[i].x * rstd * gg.x * (1.0f + scv.x) + shv.x, o1 = v[i].y * rstd * gg.y * (1.0f + scv.y) + shv.y;
;             const float o2 = v[i].z * rstd * gg.z * (1.0f + scv.z) + shv.z, o3 = v[i].w * rstd * gg.w * (1.0f + scv.w) + shv.w;
;             uint2 w; w.x = pk2(o0, o1); w.y = pk2(o2, o3);
;             *(uint2*)(A + (size_t)row * 1024 + k) = w;
;         }
; #pragma unroll
;         for (int i = 0; i < 4; ++i) v[i] = nv[i];
;         row = nrow;
;     }
	v_pk_mul_f32 v[242:243], v[172:173], v[172:173]
	v_pk_mul_f32 v[244:245], v[176:177], v[176:177]
	v_pk_mul_f32 v[246:247], v[174:175], v[174:175]
	v_pk_mul_f32 v[248:249], v[178:179], v[178:179]
	v_add_f32_e32 v204, v245, v244
	v_add_f32_e32 v205, v243, v242
	v_add_f32_e32 v204, v248, v204
	v_add_f32_e32 v205, v246, v205
	v_add_f32_e32 v204, v249, v204
	v_add_f32_e32 v205, v247, v205
	v_pk_mul_f32 v[242:243], v[180:181], v[180:181]
	v_pk_mul_f32 v[244:245], v[184:185], v[184:185]
	v_pk_mul_f32 v[246:247], v[182:183], v[182:183]
	v_pk_mul_f32 v[248:249], v[186:187], v[186:187]
	v_add_f32_e32 v206, v243, v242
	v_add_f32_e32 v207, v245, v244
	v_add_f32_e32 v206, v246, v206
	v_add_f32_e32 v207, v248, v207
	v_add_f32_e32 v206, v247, v206
	v_add_f32_e32 v207, v249, v207
	v_add_f32_e32 v204, v205, v204
	v_add_f32_e32 v204, v204, v206
	v_add_f32_e32 v204, v204, v207
	ds_swizzle_b32 v205, v204 offset:swizzle(SWAP,1)
	s_waitcnt lgkmcnt(0)
	v_add_f32_e32 v204, v204, v205
	ds_swizzle_b32 v205, v204 offset:swizzle(SWAP,2)
	s_waitcnt lgkmcnt(0)
	v_add_f32_e32 v204, v204, v205
	ds_swizzle_b32 v205, v204 offset:swizzle(SWAP,4)
	s_waitcnt lgkmcnt(0)
	v_add_f32_e32 v204, v204, v205
	ds_swizzle_b32 v205, v204 offset:swizzle(SWAP,8)
	s_waitcnt lgkmcnt(0)
	v_add_f32_e32 v204, v204, v205
	ds_swizzle_b32 v205, v204 offset:swizzle(SWAP,16)
	s_waitcnt lgkmcnt(0)
	v_add_f32_e32 v204, v204, v205
	v_mov_b32_e32 v205, v204
	s_nop 1
	v_permlane32_swap_b32_e32 v204, v205
	v_add_f32_e32 v204, v204, v205
	v_mov_b32_e32 v205, 0x358637bd
	v_fmamk_f32 v204, v204, 0x3a800000, v205
	v_rsq_f32_e32 v204, v204
	s_nop 0
	v_pk_mul_f32 v[172:173], v[172:173], v[204:205] op_sel_hi:[1,0]
	v_pk_mul_f32 v[174:175], v[174:175], v[204:205] op_sel_hi:[1,0]
	v_pk_mul_f32 v[172:173], v[188:189], v[172:173]
	v_pk_mul_f32 v[174:175], v[190:191], v[174:175]
	v_pk_fma_f32 v[172:173], v[34:35], v[172:173], v[224:225]
	v_pk_fma_f32 v[174:175], v[36:37], v[174:175], v[226:227]
	v_cvt_pk_bf16_f32 v172, v172, v173
	v_cvt_pk_bf16_f32 v173, v174, v175
	global_store_dwordx2 v146, v[172:173], s[66:67]
	v_pk_mul_f32 v[176:177], v[176:177], v[204:205] op_sel_hi:[1,0]
	v_pk_mul_f32 v[178:179], v[178:179], v[204:205] op_sel_hi:[1,0]
	v_pk_mul_f32 v[176:177], v[192:193], v[176:177]
	v_pk_mul_f32 v[178:179], v[194:195], v[178:179]
	v_pk_fma_f32 v[176:177], v[38:39], v[176:177], v[228:229]
	v_pk_fma_f32 v[178:179], v[40:41], v[178:179], v[230:231]
	v_cvt_pk_bf16_f32 v176, v176, v177
	v_cvt_pk_bf16_f32 v177, v178, v179
	global_store_dwordx2 v146, v[176:177], s[66:67] offset:512
	v_pk_mul_f32 v[180:181], v[180:181], v[204:205] op_sel_hi:[1,0]
	v_pk_mul_f32 v[182:183], v[182:183], v[204:205] op_sel_hi:[1,0]
	v_pk_mul_f32 v[180:181], v[196:197], v[180:181]
	v_pk_mul_f32 v[182:183], v[198:199], v[182:183]
	v_pk_fma_f32 v[180:181], v[42:43], v[180:181], v[232:233]
	v_pk_fma_f32 v[182:183], v[44:45], v[182:183], v[234:235]
	v_cvt_pk_bf16_f32 v180, v180, v181
	v_cvt_pk_bf16_f32 v181, v182, v183
	global_store_dwordx2 v146, v[180:181], s[66:67] offset:1024
	v_pk_mul_f32 v[184:185], v[184:185], v[204:205] op_sel_hi:[1,0]
	v_pk_mul_f32 v[186:187], v[186:187], v[204:205] op_sel_hi:[1,0]
	v_pk_mul_f32 v[184:185], v[200:201], v[184:185]
	v_pk_mul_f32 v[186:187], v[202:203], v[186:187]
	v_pk_fma_f32 v[184:185], v[46:47], v[184:185], v[236:237]
	v_pk_fma_f32 v[186:187], v[48:49], v[186:187], v[238:239]
	v_cvt_pk_bf16_f32 v184, v184, v185
	v_cvt_pk_bf16_f32 v185, v186, v187
	global_store_dwordx2 v146, v[184:185], s[66:67] offset:1536
	v_add_u32_e32 v146, 0x800, v146
	global_load_dwordx4 v[172:175], v144, s[46:47] nt
	global_load_dwordx4 v[176:179], v144, s[46:47] offset:1024 nt
	global_load_dwordx4 v[180:183], v144, s[46:47] offset:2048 nt
	global_load_dwordx4 v[184:187], v144, s[46:47] offset:3072 nt
	v_add_u32_e32 v144, 0x1000, v144
	s_waitcnt vmcnt(40)
	v_pk_mul_f32 v[242:243], v[80:81], v[80:81]
	v_pk_mul_f32 v[244:245], v[84:85], v[84:85]
	v_pk_mul_f32 v[246:247], v[82:83], v[82:83]
	v_pk_mul_f32 v[248:249], v[86:87], v[86:87]
	v_add_f32_e32 v204, v245, v244
	v_add_f32_e32 v205, v243, v242
	v_add_f32_e32 v204, v248, v204
	v_add_f32_e32 v205, v246, v205
	v_add_f32_e32 v204, v249, v204
	v_add_f32_e32 v205, v247, v205
	v_pk_mul_f32 v[242:243], v[88:89], v[88:89]
	v_pk_mul_f32 v[244:245], v[92:93], v[92:93]
	v_pk_mul_f32 v[246:247], v[90:91], v[90:91]
	v_pk_mul_f32 v[248:249], v[94:95], v[94:95]
	v_add_f32_e32 v206, v243, v242
	v_add_f32_e32 v207, v245, v244
	v_add_f32_e32 v206, v246, v206
	v_add_f32_e32 v207, v248, v207
	v_add_f32_e32 v206, v247, v206
	v_add_f32_e32 v207, v249, v207
	v_add_f32_e32 v204, v205, v204
	v_add_f32_e32 v204, v204, v206
	v_add_f32_e32 v204, v204, v207
	ds_swizzle_b32 v205, v204 offset:swizzle(SWAP,1)
	s_waitcnt lgkmcnt(0)
	v_add_f32_e32 v204, v204, v205
	ds_swizzle_b32 v205, v204 offset:swizzle(SWAP,2)
	s_waitcnt lgkmcnt(0)
	v_add_f32_e32 v204, v204, v205
	ds_swizzle_b32 v205, v204 offset:swizzle(SWAP,4)
	s_waitcnt lgkmcnt(0)
	v_add_f32_e32 v204, v204, v205
	ds_swizzle_b32 v205, v204 offset:swizzle(SWAP,8)
	s_waitcnt lgkmcnt(0)
	v_add_f32_e32 v204, v204, v205
	ds_swizzle_b32 v205, v204 offset:swizzle(SWAP,16)
	s_waitcnt lgkmcnt(0)
; __device__ __forceinline__ unsigned pk2(float lo, float hi) { const g_f32x2 f = {lo, hi}; return __builtin_bit_cast(unsigned, __builtin_convertvector(f, g_bf16x2)); }
; __device__ __forceinline__ void p_norm(const float* hlat, const float* hctx, const float* g, const float* modl, int sh_off, int sc_off, bf16_t* A, int M,
;                                        const float* part, const float* cgate, float* hcout) {
;     ...
;         float ss = 0.f;
; #pragma unroll
;         for (int i = 0; i < 4; ++i) {
;             if (part != nullptr && row >= NLAT) {
;                 const size_t po = (size_t)(row - NLAT) * 1024 + i * 256 + lane * 4;
;                 const float4 p0 = *(const float4*)(part + po), p1 = *(const float4*)(part + (size_t)4096 * 1024 + po), cg = *(const float4*)(cgate + i * 256 + lane * 4);
;                 v[i].x += cg.x * (p0.x + p1.x); v[i].y += cg.y * (p0.y + p1.y); v[i].z += cg.z * (p0.z + p1.z); v[i].w += cg.w * (p0.w + p1.w);
;                 *(float4*)(hcout + po) = v[i];
;             }
;             ss += v[i].x * v[i].x + v[i].y * v[i].y + v[i].z * v[i].z + v[i].w * v[i].w; }
;         ss = wave_sum(ss);
;         const float rstd = rsqrtf(ss * (1.0f / 1024.0f) + EPS);
;         const float* mr = modl + (size_t)r * 6144;
; #pragma unroll
;         for (int i = 0; i < 4; ++i) {
;             const int k = i * 256 + lane * 4;
;             const float4 gg = *(const float4*)(g + k), scv = *(const float4*)(mr + sc_off + k), shv = *(const float4*)(mr + sh_off + k);
;             const float o0 = v[i].x * rstd * gg.x * (1.0f + scv.x) + shv.x, o1 = v[i].y * rstd * gg.y * (1.0f + scv.y) + shv.y;
;             const float o2 = v[i].z * rstd * gg.z * (1.0f + scv.z) + shv.z, o3 = v[i].w * rstd * gg.w * (1.0f + scv.w) + shv.w;
;             uint2 w; w.x = pk2(o0, o1); w.y = pk2(o2, o3);
;             *(uint2*)(A + (size_t)row * 1024 + k) = w;
;         }
; #pragma unroll
;         for (int i = 0; i < 4; ++i) v[i] = nv[i];
;         row = nrow;
;     }
	v_add_f32_e32 v204, v204, v205
	v_mov_b32_e32 v205, v204
	s_nop 1
	v_permlane32_swap_b32_e32 v204, v205
	v_add_f32_e32 v204, v204, v205
	v_mov_b32_e32 v205, 0x358637bd
	v_fmamk_f32 v204, v204, 0x3a800000, v205
	v_rsq_f32_e32 v204, v204
	s_nop 0
	v_pk_mul_f32 v[80:81], v[80:81], v[204:205] op_sel_hi:[1,0]
	v_pk_mul_f32 v[82:83], v[82:83], v[204:205] op_sel_hi:[1,0]
	v_pk_mul_f32 v[80:81], v[188:189], v[80:81]
	v_pk_mul_f32 v[82:83], v[190:191], v[82:83]
	v_pk_fma_f32 v[80:81], v[34:35], v[80:81], v[224:225]
	v_pk_fma_f32 v[82:83], v[36:37], v[82:83], v[226:227]
	v_cvt_pk_bf16_f32 v80, v80, v81
	v_cvt_pk_bf16_f32 v81, v82, v83
	global_store_dwordx2 v146, v[80:81], s[66:67]
	v_pk_mul_f32 v[84:85], v[84:85], v[204:205] op_sel_hi:[1,0]
	v_pk_mul_f32 v[86:87], v[86:87], v[204:205] op_sel_hi:[1,0]
	v_pk_mul_f32 v[84:85], v[192:193], v[84:85]
	v_pk_mul_f32 v[86:87], v[194:195], v[86:87]
	v_pk_fma_f32 v[84:85], v[38:39], v[84:85], v[228:229]
	v_pk_fma_f32 v[86:87], v[40:41], v[86:87], v[230:231]
	v_cvt_pk_bf16_f32 v84, v84, v85
	v_cvt_pk_bf16_f32 v85, v86, v87
	global_store_dwordx2 v146, v[84:85], s[66:67] offset:512
	v_pk_mul_f32 v[88:89], v[88:89], v[204:205] op_sel_hi:[1,0]
	v_pk_mul_f32 v[90:91], v[90:91], v[204:205] op_sel_hi:[1,0]
	v_pk_mul_f32 v[88:89], v[196:197], v[88:89]
	v_pk_mul_f32 v[90:91], v[198:199], v[90:91]
	v_pk_fma_f32 v[88:89], v[42:43], v[88:89], v[232:233]
	v_pk_fma_f32 v[90:91], v[44:45], v[90:91], v[234:235]
	v_cvt_pk_bf16_f32 v88, v88, v89
	v_cvt_pk_bf16_f32 v89, v90, v91
	global_store_dwordx2 v146, v[88:89], s[66:67] offset:1024
	v_pk_mul_f32 v[92:93], v[92:93], v[204:205] op_sel_hi:[1,0]
	v_pk_mul_f32 v[94:95], v[94:95], v[204:205] op_sel_hi:[1,0]
	v_pk_mul_f32 v[92:93], v[200:201], v[92:93]
	v_pk_mul_f32 v[94:95], v[202:203], v[94:95]
	v_pk_fma_f32 v[92:93], v[46:47], v[92:93], v[236:237]
	v_pk_fma_f32 v[94:95], v[48:49], v[94:95], v[238:239]
	v_cvt_pk_bf16_f32 v92, v92, v93
	v_cvt_pk_bf16_f32 v93, v94, v95
	global_store_dwordx2 v146, v[92:93], s[66:67] offset:1536
	v_add_u32_e32 v146, 0x800, v146
	global_load_dwordx4 v[80:83], v144, s[46:47] nt
	global_load_dwordx4 v[84:87], v144, s[46:47] offset:1024 nt
	global_load_dwordx4 v[88:91], v144, s[46:47] offset:2048 nt
	global_load_dwordx4 v[92:95], v144, s[46:47] offset:3072 nt
	v_add_u32_e32 v144, 0x1000, v144
	s_waitcnt vmcnt(40)
	v_pk_mul_f32 v[242:243], v[96:97], v[96:97]
	v_pk_mul_f32 v[244:245], v[100:101], v[100:101]
	v_pk_mul_f32 v[246:247], v[98:99], v[98:99]
	v_pk_mul_f32 v[248:249], v[102:103], v[102:103]
	v_add_f32_e32 v204, v245, v244
	v_add_f32_e32 v205, v243, v242
	v_add_f32_e32 v204, v248, v204
	v_add_f32_e32 v205, v246, v205
	v_add_f32_e32 v204, v249, v204
	v_add_f32_e32 v205, v247, v205
	v_pk_mul_f32 v[242:243], v[104:105], v[104:105]
	v_pk_mul_f32 v[244:245], v[108:109], v[108:109]
	v_pk_mul_f32 v[246:247], v[106:107], v[106:107]
	v_pk_mul_f32 v[248:249], v[110:111], v[110:111]
	v_add_f32_e32 v206, v243, v242
	v_add_f32_e32 v207, v245, v244
	v_add_f32_e32 v206, v246, v206
	v_add_f32_e32 v207, v248, v207
	v_add_f32_e32 v206, v247, v206
	v_add_f32_e32 v207, v249, v207
	v_add_f32_e32 v204, v205, v204
	v_add_f32_e32 v204, v204, v206
	v_add_f32_e32 v204, v204, v207
	ds_swizzle_b32 v205, v204 offset:swizzle(SWAP,1)
	s_waitcnt lgkmcnt(0)
	v_add_f32_e32 v204, v204, v205
	ds_swizzle_b32 v205, v204 offset:swizzle(SWAP,2)
	s_waitcnt lgkmcnt(0)
	v_add_f32_e32 v204, v204, v205
	ds_swizzle_b32 v205, v204 offset:swizzle(SWAP,4)
	s_waitcnt lgkmcnt(0)
	v_add_f32_e32 v204, v204, v205
	ds_swizzle_b32 v205, v204 offset:swizzle(SWAP,8)
	s_waitcnt lgkmcnt(0)
	v_add_f32_e32 v204, v204, v205
	ds_swizzle_b32 v205, v204 offset:swizzle(SWAP,16)
	s_waitcnt lgkmcnt(0)
	v_add_f32_e32 v204, v204, v205
	v_mov_b32_e32 v205, v204
	s_nop 1
	v_permlane32_swap_b32_e32 v204, v205
	v_add_f32_e32 v204, v204, v205
	v_mov_b32_e32 v205, 0x358637bd
	v_fmamk_f32 v204, v204, 0x3a800000, v205
	v_rsq_f32_e32 v204, v204
	s_nop 0
	v_pk_mul_f32 v[96:97], v[96:97], v[204:205] op_sel_hi:[1,0]
	v_pk_mul_f32 v[98:99], v[98:99], v[204:205] op_sel_hi:[1,0]
	v_pk_mul_f32 v[96:97], v[188:189], v[96:97]
	v_pk_mul_f32 v[98:99], v[190:191], v[98:99]
	v_pk_fma_f32 v[96:97], v[34:35], v[96:97], v[224:225]
	v_pk_fma_f32 v[98:99], v[36:37], v[98:99], v[226:227]
	v_cvt_pk_bf16_f32 v96, v96, v97
	v_cvt_pk_bf16_f32 v97, v98, v99
	global_store_dwordx2 v146, v[96:97], s[66:67]
	v_pk_mul_f32 v[100:101], v[100:101], v[204:205] op_sel_hi:[1,0]
	v_pk_mul_f32 v[102:103], v[102:103], v[204:205] op_sel_hi:[1,0]
	v_pk_mul_f32 v[100:101], v[192:193], v[100:101]
	v_pk_mul_f32 v[102:103], v[194:195], v[102:103]
	v_pk_fma_f32 v[100:101], v[38:39], v[100:101], v[228:229]
	v_pk_fma_f32 v[102:103], v[40:41], v[102:103], v[230:231]
	v_cvt_pk_bf16_f32 v100, v100, v101
	v_cvt_pk_bf16_f32 v101, v102, v103
	global_store_dwordx2 v146, v[100:101], s[66:67] offset:512
	v_pk_mul_f32 v[104:105], v[104:105], v[204:205] op_sel_hi:[1,0]
	v_pk_mul_f32 v[106:107], v[106:107], v[204:205] op_sel_hi:[1,0]
	v_pk_mul_f32 v[104:105], v[196:197], v[104:105]
	v_pk_mul_f32 v[106:107], v[198:199], v[106:107]
	v_pk_fma_f32 v[104:105], v[42:43], v[104:105], v[232:233]
	v_pk_fma_f32 v[106:107], v[44:45], v[106:107], v[234:235]
	v_cvt_pk_bf16_f32 v104, v104, v105
	v_cvt_pk_bf16_f32 v105, v106, v107
	global_store_dwordx2 v146, v[104:105], s[66:67] offset:1024
	v_pk_mul_f32 v[108:109], v[108:109], v[204:205] op_sel_hi:[1,0]
	v_pk_mul_f32 v[110:111], v[110:111], v[204:205] op_sel_hi:[1,0]
	v_pk_mul_f32 v[108:109], v[200:201], v[108:109]
	v_pk_mul_f32 v[110:111], v[202:203], v[110:111]
	v_pk_fma_f32 v[108:109], v[46:47], v[108:109], v[236:237]
	v_pk_fma_f32 v[110:111], v[48:49], v[110:111], v[238:239]
	v_cvt_pk_bf16_f32 v108, v108, v109
	v_cvt_pk_bf16_f32 v109, v110, v111
	global_store_dwordx2 v146, v[108:109], s[66:67] offset:1536
	v_add_u32_e32 v146, 0x800, v146
	global_load_dwordx4 v[96:99], v144, s[46:47] nt
	global_load_dwordx4 v[100:103], v144, s[46:47] offset:1024 nt
	global_load_dwordx4 v[104:107], v144, s[46:47] offset:2048 nt
	global_load_dwordx4 v[108:111], v144, s[46:47] offset:3072 nt
	v_add_u32_e32 v144, 0x1000, v144
	s_waitcnt vmcnt(40)
; __device__ __forceinline__ unsigned pk2(float lo, float hi) { const g_f32x2 f = {lo, hi}; return __builtin_bit_cast(unsigned, __builtin_convertvector(f, g_bf16x2)); }
; __device__ __forceinline__ void p_norm(const float* hlat, const float* hctx, const float* g, const float* modl, int sh_off, int sc_off, bf16_t* A, int M,
;                                        const float* part, const float* cgate, float* hcout) {
;     ...
;         float ss = 0.f;
; #pragma unroll
;         for (int i = 0; i < 4; ++i) {
;             if (part != nullptr && row >= NLAT) {
;                 const size_t po = (size_t)(row - NLAT) * 1024 + i * 256 + lane * 4;
;                 const float4 p0 = *(const float4*)(part + po), p1 = *(const float4*)(part + (size_t)4096 * 1024 + po), cg = *(const float4*)(cgate + i * 256 + lane * 4);
;                 v[i].x += cg.x * (p0.x + p1.x); v[i].y += cg.y * (p0.y + p1.y); v[i].z += cg.z * (p0.z + p1.z); v[i].w += cg.w * (p0.w + p1.w);
;                 *(float4*)(hcout + po) = v[i];
;             }
;             ss += v[i].x * v[i].x + v[i].y * v[i].y + v[i].z * v[i].z + v[i].w * v[i].w; }
;         ss = wave_sum(ss);
;         const float rstd = rsqrtf(ss * (1.0f / 1024.0f) + EPS);
;         const float* mr = modl + (size_t)r * 6144;
; #pragma unroll
;         for (int i = 0; i < 4; ++i) {
;             const int k = i * 256 + lane * 4;
;             const float4 gg = *(const float4*)(g + k), scv = *(const float4*)(mr + sc_off + k), shv = *(const float4*)(mr + sh_off + k);
;             const float o0 = v[i].x * rstd * gg.x * (1.0f + scv.x) + shv.x, o1 = v[i].y * rstd * gg.y * (1.0f + scv.y) + shv.y;
;             const float o2 = v[i].z * rstd * gg.z * (1.0f + scv.z) + shv.z, o3 = v[i].w * rstd * gg.w * (1.0f + scv.w) + shv.w;
;             uint2 w; w.x = pk2(o0, o1); w.y = pk2(o2, o3);
;             *(uint2*)(A + (size_t)row * 1024 + k) = w;
;         }
; #pragma unroll
;         for (int i = 0; i < 4; ++i) v[i] = nv[i];
;         row = nrow;
;     }
	v_pk_mul_f32 v[242:243], v[112:113], v[112:113]
	v_pk_mul_f32 v[244:245], v[116:117], v[116:117]
	v_pk_mul_f32 v[246:247], v[114:115], v[114:115]
	v_pk_mul_f32 v[248:249], v[118:119], v[118:119]
	v_add_f32_e32 v204, v245, v244
	v_add_f32_e32 v205, v243, v242
	v_add_f32_e32 v204, v248, v204
	v_add_f32_e32 v205, v246, v205
	v_add_f32_e32 v204, v249, v204
	v_add_f32_e32 v205, v247, v205
	v_pk_mul_f32 v[242:243], v[120:121], v[120:121]
	v_pk_mul_f32 v[244:245], v[124:125], v[124:125]
	v_pk_mul_f32 v[246:247], v[122:123], v[122:123]
	v_pk_mul_f32 v[248:249], v[126:127], v[126:127]
	v_add_f32_e32 v206, v243, v242
	v_add_f32_e32 v207, v245, v244
	v_add_f32_e32 v206, v246, v206
	v_add_f32_e32 v207, v248, v207
	v_add_f32_e32 v206, v247, v206
	v_add_f32_e32 v207, v249, v207
	v_add_f32_e32 v204, v205, v204
	v_add_f32_e32 v204, v204, v206
	v_add_f32_e32 v204, v204, v207
	ds_swizzle_b32 v205, v204 offset:swizzle(SWAP,1)
	s_waitcnt lgkmcnt(0)
	v_add_f32_e32 v204, v204, v205
	ds_swizzle_b32 v205, v204 offset:swizzle(SWAP,2)
	s_waitcnt lgkmcnt(0)
	v_add_f32_e32 v204, v204, v205
	ds_swizzle_b32 v205, v204 offset:swizzle(SWAP,4)
	s_waitcnt lgkmcnt(0)
	v_add_f32_e32 v204, v204, v205
	ds_swizzle_b32 v205, v204 offset:swizzle(SWAP,8)
	s_waitcnt lgkmcnt(0)
	v_add_f32_e32 v204, v204, v205
	ds_swizzle_b32 v205, v204 offset:swizzle(SWAP,16)
	s_waitcnt lgkmcnt(0)
	v_add_f32_e32 v204, v204, v205
	v_mov_b32_e32 v205, v204
	s_nop 1
	v_permlane32_swap_b32_e32 v204, v205
	v_add_f32_e32 v204, v204, v205
	v_mov_b32_e32 v205, 0x358637bd
	v_fmamk_f32 v204, v204, 0x3a800000, v205
	v_rsq_f32_e32 v204, v204
	s_nop 0
	v_pk_mul_f32 v[112:113], v[112:113], v[204:205] op_sel_hi:[1,0]
	v_pk_mul_f32 v[114:115], v[114:115], v[204:205] op_sel_hi:[1,0]
	v_pk_mul_f32 v[112:113], v[188:189], v[112:113]
	v_pk_mul_f32 v[114:115], v[190:191], v[114:115]
	v_pk_fma_f32 v[112:113], v[34:35], v[112:113], v[224:225]
	v_pk_fma_f32 v[114:115], v[36:37], v[114:115], v[226:227]
	v_cvt_pk_bf16_f32 v112, v112, v113
	v_cvt_pk_bf16_f32 v113, v114, v115
	global_store_dwordx2 v146, v[112:113], s[66:67]
	v_pk_mul_f32 v[116:117], v[116:117], v[204:205] op_sel_hi:[1,0]
	v_pk_mul_f32 v[118:119], v[118:119], v[204:205] op_sel_hi:[1,0]
	v_pk_mul_f32 v[116:117], v[192:193], v[116:117]
	v_pk_mul_f32 v[118:119], v[194:195], v[118:119]
	v_pk_fma_f32 v[116:117], v[38:39], v[116:117], v[228:229]
	v_pk_fma_f32 v[118:119], v[40:41], v[118:119], v[230:231]
	v_cvt_pk_bf16_f32 v116, v116, v117
	v_cvt_pk_bf16_f32 v117, v118, v119
	global_store_dwordx2 v146, v[116:117], s[66:67] offset:512
	v_pk_mul_f32 v[120:121], v[120:121], v[204:205] op_sel_hi:[1,0]
	v_pk_mul_f32 v[122:123], v[122:123], v[204:205] op_sel_hi:[1,0]
	v_pk_mul_f32 v[120:121], v[196:197], v[120:121]
	v_pk_mul_f32 v[122:123], v[198:199], v[122:123]
	v_pk_fma_f32 v[120:121], v[42:43], v[120:121], v[232:233]
	v_pk_fma_f32 v[122:123], v[44:45], v[122:123], v[234:235]
	v_cvt_pk_bf16_f32 v120, v120, v121
	v_cvt_pk_bf16_f32 v121, v122, v123
	global_store_dwordx2 v146, v[120:121], s[66:67] offset:1024
	v_pk_mul_f32 v[124:125], v[124:125], v[204:205] op_sel_hi:[1,0]
	v_pk_mul_f32 v[126:127], v[126:127], v[204:205] op_sel_hi:[1,0]
	v_pk_mul_f32 v[124:125], v[200:201], v[124:125]
	v_pk_mul_f32 v[126:127], v[202:203], v[126:127]
	v_pk_fma_f32 v[124:125], v[46:47], v[124:125], v[236:237]
	v_pk_fma_f32 v[126:127], v[48:49], v[126:127], v[238:239]
	v_cvt_pk_bf16_f32 v124, v124, v125
	v_cvt_pk_bf16_f32 v125, v126, v127
	global_store_dwordx2 v146, v[124:125], s[66:67] offset:1536
	v_add_u32_e32 v146, 0x800, v146
	global_load_dwordx4 v[112:115], v144, s[46:47] nt
	global_load_dwordx4 v[116:119], v144, s[46:47] offset:1024 nt
	global_load_dwordx4 v[120:123], v144, s[46:47] offset:2048 nt
	global_load_dwordx4 v[124:127], v144, s[46:47] offset:3072 nt
	v_add_u32_e32 v144, 0x1000, v144
	s_waitcnt vmcnt(40)
	v_pk_mul_f32 v[242:243], v[128:129], v[128:129]
	v_pk_mul_f32 v[244:245], v[132:133], v[132:133]
	v_pk_mul_f32 v[246:247], v[130:131], v[130:131]
	v_pk_mul_f32 v[248:249], v[134:135], v[134:135]
	v_add_f32_e32 v204, v245, v244
	v_add_f32_e32 v205, v243, v242
	v_add_f32_e32 v204, v248, v204
	v_add_f32_e32 v205, v246, v205
	v_add_f32_e32 v204, v249, v204
	v_add_f32_e32 v205, v247, v205
	v_pk_mul_f32 v[242:243], v[136:137], v[136:137]
	v_pk_mul_f32 v[244:245], v[140:141], v[140:141]
	v_pk_mul_f32 v[246:247], v[138:139], v[138:139]
	v_pk_mul_f32 v[248:249], v[142:143], v[142:143]
	v_add_f32_e32 v206, v243, v242
	v_add_f32_e32 v207, v245, v244
	v_add_f32_e32 v206, v246, v206
	v_add_f32_e32 v207, v248, v207
	v_add_f32_e32 v206, v247, v206
	v_add_f32_e32 v207, v249, v207
	v_add_f32_e32 v204, v205, v204
	v_add_f32_e32 v204, v204, v206
	v_add_f32_e32 v204, v204, v207
	ds_swizzle_b32 v205, v204 offset:swizzle(SWAP,1)
	s_waitcnt lgkmcnt(0)
	v_add_f32_e32 v204, v204, v205
	ds_swizzle_b32 v205, v204 offset:swizzle(SWAP,2)
	s_waitcnt lgkmcnt(0)
	v_add_f32_e32 v204, v204, v205
	ds_swizzle_b32 v205, v204 offset:swizzle(SWAP,4)
	s_waitcnt lgkmcnt(0)
	v_add_f32_e32 v204, v204, v205
	ds_swizzle_b32 v205, v204 offset:swizzle(SWAP,8)
	s_waitcnt lgkmcnt(0)
	v_add_f32_e32 v204, v204, v205
	ds_swizzle_b32 v205, v204 offset:swizzle(SWAP,16)
	s_waitcnt lgkmcnt(0)
; __device__ __forceinline__ unsigned pk2(float lo, float hi) { const g_f32x2 f = {lo, hi}; return __builtin_bit_cast(unsigned, __builtin_convertvector(f, g_bf16x2)); }
; __device__ __forceinline__ void p_norm(const float* hlat, const float* hctx, const float* g, const float* modl, int sh_off, int sc_off, bf16_t* A, int M,
;                                        const float* part, const float* cgate, float* hcout) {
;     ...
;         float ss = 0.f;
; #pragma unroll
;         for (int i = 0; i < 4; ++i) {
;             if (part != nullptr && row >= NLAT) {
;                 const size_t po = (size_t)(row - NLAT) * 1024 + i * 256 + lane * 4;
;                 const float4 p0 = *(const float4*)(part + po), p1 = *(const float4*)(part + (size_t)4096 * 1024 + po), cg = *(const float4*)(cgate + i * 256 + lane * 4);
;                 v[i].x += cg.x * (p0.x + p1.x); v[i].y += cg.y * (p0.y + p1.y); v[i].z += cg.z * (p0.z + p1.z); v[i].w += cg.w * (p0.w + p1.w);
;                 *(float4*)(hcout + po) = v[i];
;             }
;             ss += v[i].x * v[i].x + v[i].y * v[i].y + v[i].z * v[i].z + v[i].w * v[i].w; }
;         ss = wave_sum(ss);
;         const float rstd = rsqrtf(ss * (1.0f / 1024.0f) + EPS);
;         const float* mr = modl + (size_t)r * 6144;
; #pragma unroll
;         for (int i = 0; i < 4; ++i) {
;             const int k = i * 256 + lane * 4;
;             const float4 gg = *(const float4*)(g + k), scv = *(const float4*)(mr + sc_off + k), shv = *(const float4*)(mr + sh_off + k);
;             const float o0 = v[i].x * rstd * gg.x * (1.0f + scv.x) + shv.x, o1 = v[i].y * rstd * gg.y * (1.0f + scv.y) + shv.y;
;             const float o2 = v[i].z * rstd * gg.z * (1.0f + scv.z) + shv.z, o3 = v[i].w * rstd * gg.w * (1.0f + scv.w) + shv.w;
;             uint2 w; w.x = pk2(o0, o1); w.y = pk2(o2, o3);
;             *(uint2*)(A + (size_t)row * 1024 + k) = w;
;         }
; #pragma unroll
;         for (int i = 0; i < 4; ++i) v[i] = nv[i];
;         row = nrow;
;     }
	v_add_f32_e32 v204, v204, v205
	v_mov_b32_e32 v205, v204
	s_nop 1
	v_permlane32_swap_b32_e32 v204, v205
	v_add_f32_e32 v204, v204, v205
	v_mov_b32_e32 v205, 0x358637bd
	v_fmamk_f32 v204, v204, 0x3a800000, v205
	v_rsq_f32_e32 v204, v204
	s_nop 0
	v_pk_mul_f32 v[128:129], v[128:129], v[204:205] op_sel_hi:[1,0]
	v_pk_mul_f32 v[130:131], v[130:131], v[204:205] op_sel_hi:[1,0]
	v_pk_mul_f32 v[128:129], v[188:189], v[128:129]
	v_pk_mul_f32 v[130:131], v[190:191], v[130:131]
	v_pk_fma_f32 v[128:129], v[34:35], v[128:129], v[224:225]
	v_pk_fma_f32 v[130:131], v[36:37], v[130:131], v[226:227]
	v_cvt_pk_bf16_f32 v128, v128, v129
	v_cvt_pk_bf16_f32 v129, v130, v131
	global_store_dwordx2 v146, v[128:129], s[66:67]
	v_pk_mul_f32 v[132:133], v[132:133], v[204:205] op_sel_hi:[1,0]
	v_pk_mul_f32 v[134:135], v[134:135], v[204:205] op_sel_hi:[1,0]
	v_pk_mul_f32 v[132:133], v[192:193], v[132:133]
	v_pk_mul_f32 v[134:135], v[194:195], v[134:135]
	v_pk_fma_f32 v[132:133], v[38:39], v[132:133], v[228:229]
	v_pk_fma_f32 v[134:135], v[40:41], v[134:135], v[230:231]
	v_cvt_pk_bf16_f32 v132, v132, v133
	v_cvt_pk_bf16_f32 v133, v134, v135
	global_store_dwordx2 v146, v[132:133], s[66:67] offset:512
	v_pk_mul_f32 v[136:137], v[136:137], v[204:205] op_sel_hi:[1,0]
	v_pk_mul_f32 v[138:139], v[138:139], v[204:205] op_sel_hi:[1,0]
	v_pk_mul_f32 v[136:137], v[196:197], v[136:137]
	v_pk_mul_f32 v[138:139], v[198:199], v[138:139]
	v_pk_fma_f32 v[136:137], v[42:43], v[136:137], v[232:233]
	v_pk_fma_f32 v[138:139], v[44:45], v[138:139], v[234:235]
	v_cvt_pk_bf16_f32 v136, v136, v137
	v_cvt_pk_bf16_f32 v137, v138, v139
	global_store_dwordx2 v146, v[136:137], s[66:67] offset:1024
	v_pk_mul_f32 v[140:141], v[140:141], v[204:205] op_sel_hi:[1,0]
	v_pk_mul_f32 v[142:143], v[142:143], v[204:205] op_sel_hi:[1,0]
	v_pk_mul_f32 v[140:141], v[200:201], v[140:141]
	v_pk_mul_f32 v[142:143], v[202:203], v[142:143]
	v_pk_fma_f32 v[140:141], v[46:47], v[140:141], v[236:237]
	v_pk_fma_f32 v[142:143], v[48:49], v[142:143], v[238:239]
	v_cvt_pk_bf16_f32 v140, v140, v141
	v_cvt_pk_bf16_f32 v141, v142, v143
	global_store_dwordx2 v146, v[140:141], s[66:67] offset:1536
	v_add_u32_e32 v146, 0x800, v146
	global_load_dwordx4 v[128:131], v144, s[46:47] nt
	global_load_dwordx4 v[132:135], v144, s[46:47] offset:1024 nt
	global_load_dwordx4 v[136:139], v144, s[46:47] offset:2048 nt
	global_load_dwordx4 v[140:143], v144, s[46:47] offset:3072 nt
	v_add_u32_e32 v144, 0x1000, v144
	s_waitcnt vmcnt(40)
	v_pk_mul_f32 v[242:243], v[156:157], v[156:157]
	v_pk_mul_f32 v[244:245], v[160:161], v[160:161]
	v_pk_mul_f32 v[246:247], v[158:159], v[158:159]
	v_pk_mul_f32 v[248:249], v[162:163], v[162:163]
	v_add_f32_e32 v204, v245, v244
	v_add_f32_e32 v205, v243, v242
	v_add_f32_e32 v204, v248, v204
	v_add_f32_e32 v205, v246, v205
	v_add_f32_e32 v204, v249, v204
	v_add_f32_e32 v205, v247, v205
	v_pk_mul_f32 v[242:243], v[164:165], v[164:165]
	v_pk_mul_f32 v[244:245], v[168:169], v[168:169]
	v_pk_mul_f32 v[246:247], v[166:167], v[166:167]
	v_pk_mul_f32 v[248:249], v[170:171], v[170:171]
	v_add_f32_e32 v206, v243, v242
	v_add_f32_e32 v207, v245, v244
	v_add_f32_e32 v206, v246, v206
	v_add_f32_e32 v207, v248, v207
	v_add_f32_e32 v206, v247, v206
	v_add_f32_e32 v207, v249, v207
	v_add_f32_e32 v204, v205, v204
	v_add_f32_e32 v204, v204, v206
	v_add_f32_e32 v204, v204, v207
	ds_swizzle_b32 v205, v204 offset:swizzle(SWAP,1)
	s_waitcnt lgkmcnt(0)
	v_add_f32_e32 v204, v204, v205
	ds_swizzle_b32 v205, v204 offset:swizzle(SWAP,2)
	s_waitcnt lgkmcnt(0)
	v_add_f32_e32 v204, v204, v205
	ds_swizzle_b32 v205, v204 offset:swizzle(SWAP,4)
	s_waitcnt lgkmcnt(0)
	v_add_f32_e32 v204, v204, v205
	ds_swizzle_b32 v205, v204 offset:swizzle(SWAP,8)
	s_waitcnt lgkmcnt(0)
	v_add_f32_e32 v204, v204, v205
	ds_swizzle_b32 v205, v204 offset:swizzle(SWAP,16)
	s_waitcnt lgkmcnt(0)
	v_add_f32_e32 v204, v204, v205
	v_mov_b32_e32 v205, v204
	s_nop 1
	v_permlane32_swap_b32_e32 v204, v205
	v_add_f32_e32 v204, v204, v205
	v_mov_b32_e32 v205, 0x358637bd
	v_fmamk_f32 v204, v204, 0x3a800000, v205
	v_rsq_f32_e32 v204, v204
	s_nop 0
	v_pk_mul_f32 v[156:157], v[156:157], v[204:205] op_sel_hi:[1,0]
	v_pk_mul_f32 v[158:159], v[158:159], v[204:205] op_sel_hi:[1,0]
	v_pk_mul_f32 v[156:157], v[188:189], v[156:157]
	v_pk_mul_f32 v[158:159], v[190:191], v[158:159]
	v_pk_fma_f32 v[156:157], v[34:35], v[156:157], v[224:225]
	v_pk_fma_f32 v[158:159], v[36:37], v[158:159], v[226:227]
	v_cvt_pk_bf16_f32 v156, v156, v157
	v_cvt_pk_bf16_f32 v157, v158, v159
	global_store_dwordx2 v146, v[156:157], s[66:67]
	v_pk_mul_f32 v[160:161], v[160:161], v[204:205] op_sel_hi:[1,0]
	v_pk_mul_f32 v[162:163], v[162:163], v[204:205] op_sel_hi:[1,0]
	v_pk_mul_f32 v[160:161], v[192:193], v[160:161]
	v_pk_mul_f32 v[162:163], v[194:195], v[162:163]
	v_pk_fma_f32 v[160:161], v[38:39], v[160:161], v[228:229]
	v_pk_fma_f32 v[162:163], v[40:41], v[162:163], v[230:231]
	v_cvt_pk_bf16_f32 v160, v160, v161
	v_cvt_pk_bf16_f32 v161, v162, v163
	global_store_dwordx2 v146, v[160:161], s[66:67] offset:512
	v_pk_mul_f32 v[164:165], v[164:165], v[204:205] op_sel_hi:[1,0]
	v_pk_mul_f32 v[166:167], v[166:167], v[204:205] op_sel_hi:[1,0]
	v_pk_mul_f32 v[164:165], v[196:197], v[164:165]
	v_pk_mul_f32 v[166:167], v[198:199], v[166:167]
	v_pk_fma_f32 v[164:165], v[42:43], v[164:165], v[232:233]
	v_pk_fma_f32 v[166:167], v[44:45], v[166:167], v[234:235]
	v_cvt_pk_bf16_f32 v164, v164, v165
	v_cvt_pk_bf16_f32 v165, v166, v167
	global_store_dwordx2 v146, v[164:165], s[66:67] offset:1024
	v_pk_mul_f32 v[168:169], v[168:169], v[204:205] op_sel_hi:[1,0]
	v_pk_mul_f32 v[170:171], v[170:171], v[204:205] op_sel_hi:[1,0]
	v_pk_mul_f32 v[168:169], v[200:201], v[168:169]
	v_pk_mul_f32 v[170:171], v[202:203], v[170:171]
	v_pk_fma_f32 v[168:169], v[46:47], v[168:169], v[236:237]
	v_pk_fma_f32 v[170:171], v[48:49], v[170:171], v[238:239]
	v_cvt_pk_bf16_f32 v168, v168, v169
	v_cvt_pk_bf16_f32 v169, v170, v171
	global_store_dwordx2 v146, v[168:169], s[66:67] offset:1536
	v_add_u32_e32 v146, 0x800, v146
	s_waitcnt vmcnt(36)
; __device__ __forceinline__ unsigned pk2(float lo, float hi) { const g_f32x2 f = {lo, hi}; return __builtin_bit_cast(unsigned, __builtin_convertvector(f, g_bf16x2)); }
; __device__ __forceinline__ void p_norm(const float* hlat, const float* hctx, const float* g, const float* modl, int sh_off, int sc_off, bf16_t* A, int M,
;                                        const float* part, const float* cgate, float* hcout) {
;     ...
;         float ss = 0.f;
; #pragma unroll
;         for (int i = 0; i < 4; ++i) {
;             if (part != nullptr && row >= NLAT) {
;                 const size_t po = (size_t)(row - NLAT) * 1024 + i * 256 + lane * 4;
;                 const float4 p0 = *(const float4*)(part + po), p1 = *(const float4*)(part + (size_t)4096 * 1024 + po), cg = *(const float4*)(cgate + i * 256 + lane * 4);
;                 v[i].x += cg.x * (p0.x + p1.x); v[i].y += cg.y * (p0.y + p1.y); v[i].z += cg.z * (p0.z + p1.z); v[i].w += cg.w * (p0.w + p1.w);
;                 *(float4*)(hcout + po) = v[i];
;             }
;             ss += v[i].x * v[i].x + v[i].y * v[i].y + v[i].z * v[i].z + v[i].w * v[i].w; }
;         ss = wave_sum(ss);
;         const float rstd = rsqrtf(ss * (1.0f / 1024.0f) + EPS);
;         const float* mr = modl + (size_t)r * 6144;
; #pragma unroll
;         for (int i = 0; i < 4; ++i) {
;             const int k = i * 256 + lane * 4;
;             const float4 gg = *(const float4*)(g + k), scv = *(const float4*)(mr + sc_off + k), shv = *(const float4*)(mr + sh_off + k);
;             const float o0 = v[i].x * rstd * gg.x * (1.0f + scv.x) + shv.x, o1 = v[i].y * rstd * gg.y * (1.0f + scv.y) + shv.y;
;             const float o2 = v[i].z * rstd * gg.z * (1.0f + scv.z) + shv.z, o3 = v[i].w * rstd * gg.w * (1.0f + scv.w) + shv.w;
;             uint2 w; w.x = pk2(o0, o1); w.y = pk2(o2, o3);
;             *(uint2*)(A + (size_t)row * 1024 + k) = w;
;         }
; #pragma unroll
;         for (int i = 0; i < 4; ++i) v[i] = nv[i];
;         row = nrow;
;     }
	v_pk_mul_f32 v[242:243], v[172:173], v[172:173]
	v_pk_mul_f32 v[244:245], v[176:177], v[176:177]
	v_pk_mul_f32 v[246:247], v[174:175], v[174:175]
	v_pk_mul_f32 v[248:249], v[178:179], v[178:179]
	v_add_f32_e32 v204, v245, v244
	v_add_f32_e32 v205, v243, v242
	v_add_f32_e32 v204, v248, v204
	v_add_f32_e32 v205, v246, v205
	v_add_f32_e32 v204, v249, v204
	v_add_f32_e32 v205, v247, v205
	v_pk_mul_f32 v[242:243], v[180:181], v[180:181]
	v_pk_mul_f32 v[244:245], v[184:185], v[184:185]
	v_pk_mul_f32 v[246:247], v[182:183], v[182:183]
	v_pk_mul_f32 v[248:249], v[186:187], v[186:187]
	v_add_f32_e32 v206, v243, v242
	v_add_f32_e32 v207, v245, v244
	v_add_f32_e32 v206, v246, v206
	v_add_f32_e32 v207, v248, v207
	v_add_f32_e32 v206, v247, v206
	v_add_f32_e32 v207, v249, v207
	v_add_f32_e32 v204, v205, v204
	v_add_f32_e32 v204, v204, v206
	v_add_f32_e32 v204, v204, v207
	ds_swizzle_b32 v205, v204 offset:swizzle(SWAP,1)
	s_waitcnt lgkmcnt(0)
	v_add_f32_e32 v204, v204, v205
	ds_swizzle_b32 v205, v204 offset:swizzle(SWAP,2)
	s_waitcnt lgkmcnt(0)
	v_add_f32_e32 v204, v204, v205
	ds_swizzle_b32 v205, v204 offset:swizzle(SWAP,4)
	s_waitcnt lgkmcnt(0)
	v_add_f32_e32 v204, v204, v205
	ds_swizzle_b32 v205, v204 offset:swizzle(SWAP,8)
	s_waitcnt lgkmcnt(0)
	v_add_f32_e32 v204, v204, v205
	ds_swizzle_b32 v205, v204 offset:swizzle(SWAP,16)
	s_waitcnt lgkmcnt(0)
	v_add_f32_e32 v204, v204, v205
	v_mov_b32_e32 v205, v204
	s_nop 1
	v_permlane32_swap_b32_e32 v204, v205
	v_add_f32_e32 v204, v204, v205
	v_mov_b32_e32 v205, 0x358637bd
	v_fmamk_f32 v204, v204, 0x3a800000, v205
	v_rsq_f32_e32 v204, v204
	s_nop 0
	v_pk_mul_f32 v[172:173], v[172:173], v[204:205] op_sel_hi:[1,0]
	v_pk_mul_f32 v[174:175], v[174:175], v[204:205] op_sel_hi:[1,0]
	v_pk_mul_f32 v[172:173], v[188:189], v[172:173]
	v_pk_mul_f32 v[174:175], v[190:191], v[174:175]
	v_pk_fma_f32 v[172:173], v[34:35], v[172:173], v[224:225]
	v_pk_fma_f32 v[174:175], v[36:37], v[174:175], v[226:227]
	v_cvt_pk_bf16_f32 v172, v172, v173
	v_cvt_pk_bf16_f32 v173, v174, v175
	global_store_dwordx2 v146, v[172:173], s[66:67]
	v_pk_mul_f32 v[176:177], v[176:177], v[204:205] op_sel_hi:[1,0]
	v_pk_mul_f32 v[178:179], v[178:179], v[204:205] op_sel_hi:[1,0]
	v_pk_mul_f32 v[176:177], v[192:193], v[176:177]
	v_pk_mul_f32 v[178:179], v[194:195], v[178:179]
	v_pk_fma_f32 v[176:177], v[38:39], v[176:177], v[228:229]
	v_pk_fma_f32 v[178:179], v[40:41], v[178:179], v[230:231]
	v_cvt_pk_bf16_f32 v176, v176, v177
	v_cvt_pk_bf16_f32 v177, v178, v179
	global_store_dwordx2 v146, v[176:177], s[66:67] offset:512
	v_pk_mul_f32 v[180:181], v[180:181], v[204:205] op_sel_hi:[1,0]
	v_pk_mul_f32 v[182:183], v[182:183], v[204:205] op_sel_hi:[1,0]
	v_pk_mul_f32 v[180:181], v[196:197], v[180:181]
	v_pk_mul_f32 v[182:183], v[198:199], v[182:183]
	v_pk_fma_f32 v[180:181], v[42:43], v[180:181], v[232:233]
	v_pk_fma_f32 v[182:183], v[44:45], v[182:183], v[234:235]
	v_cvt_pk_bf16_f32 v180, v180, v181
	v_cvt_pk_bf16_f32 v181, v182, v183
	global_store_dwordx2 v146, v[180:181], s[66:67] offset:1024
	v_pk_mul_f32 v[184:185], v[184:185], v[204:205] op_sel_hi:[1,0]
	v_pk_mul_f32 v[186:187], v[186:187], v[204:205] op_sel_hi:[1,0]
	v_pk_mul_f32 v[184:185], v[200:201], v[184:185]
	v_pk_mul_f32 v[186:187], v[202:203], v[186:187]
	v_pk_fma_f32 v[184:185], v[46:47], v[184:185], v[236:237]
	v_pk_fma_f32 v[186:187], v[48:49], v[186:187], v[238:239]
	v_cvt_pk_bf16_f32 v184, v184, v185
	v_cvt_pk_bf16_f32 v185, v186, v187
	global_store_dwordx2 v146, v[184:185], s[66:67] offset:1536
	v_add_u32_e32 v146, 0x800, v146
	s_waitcnt vmcnt(32)
	v_pk_mul_f32 v[242:243], v[80:81], v[80:81]
	v_pk_mul_f32 v[244:245], v[84:85], v[84:85]
	v_pk_mul_f32 v[246:247], v[82:83], v[82:83]
	v_pk_mul_f32 v[248:249], v[86:87], v[86:87]
	v_add_f32_e32 v204, v245, v244
	v_add_f32_e32 v205, v243, v242
	v_add_f32_e32 v204, v248, v204
	v_add_f32_e32 v205, v246, v205
	v_add_f32_e32 v204, v249, v204
	v_add_f32_e32 v205, v247, v205
	v_pk_mul_f32 v[242:243], v[88:89], v[88:89]
	v_pk_mul_f32 v[244:245], v[92:93], v[92:93]
	v_pk_mul_f32 v[246:247], v[90:91], v[90:91]
	v_pk_mul_f32 v[248:249], v[94:95], v[94:95]
	v_add_f32_e32 v206, v243, v242
	v_add_f32_e32 v207, v245, v244
	v_add_f32_e32 v206, v246, v206
	v_add_f32_e32 v207, v248, v207
	v_add_f32_e32 v206, v247, v206
	v_add_f32_e32 v207, v249, v207
	v_add_f32_e32 v204, v205, v204
	v_add_f32_e32 v204, v204, v206
	v_add_f32_e32 v204, v204, v207
	ds_swizzle_b32 v205, v204 offset:swizzle(SWAP,1)
	s_waitcnt lgkmcnt(0)
	v_add_f32_e32 v204, v204, v205
	ds_swizzle_b32 v205, v204 offset:swizzle(SWAP,2)
	s_waitcnt lgkmcnt(0)
	v_add_f32_e32 v204, v204, v205
	ds_swizzle_b32 v205, v204 offset:swizzle(SWAP,4)
	s_waitcnt lgkmcnt(0)
	v_add_f32_e32 v204, v204, v205
	ds_swizzle_b32 v205, v204 offset:swizzle(SWAP,8)
	s_waitcnt lgkmcnt(0)
	v_add_f32_e32 v204, v204, v205
	ds_swizzle_b32 v205, v204 offset:swizzle(SWAP,16)
	s_waitcnt lgkmcnt(0)
; __device__ __forceinline__ unsigned pk2(float lo, float hi) { const g_f32x2 f = {lo, hi}; return __builtin_bit_cast(unsigned, __builtin_convertvector(f, g_bf16x2)); }
; __device__ __forceinline__ void p_norm(const float* hlat, const float* hctx, const float* g, const float* modl, int sh_off, int sc_off, bf16_t* A, int M,
;                                        const float* part, const float* cgate, float* hcout) {
;     ...
;         float ss = 0.f;
; #pragma unroll
;         for (int i = 0; i < 4; ++i) {
;             if (part != nullptr && row >= NLAT) {
;                 const size_t po = (size_t)(row - NLAT) * 1024 + i * 256 + lane * 4;
;                 const float4 p0 = *(const float4*)(part + po), p1 = *(const float4*)(part + (size_t)4096 * 1024 + po), cg = *(const float4*)(cgate + i * 256 + lane * 4);
;                 v[i].x += cg.x * (p0.x + p1.x); v[i].y += cg.y * (p0.y + p1.y); v[i].z += cg.z * (p0.z + p1.z); v[i].w += cg.w * (p0.w + p1.w);
;                 *(float4*)(hcout + po) = v[i];
;             }
;             ss += v[i].x * v[i].x + v[i].y * v[i].y + v[i].z * v[i].z + v[i].w * v[i].w; }
;         ss = wave_sum(ss);
;         const float rstd = rsqrtf(ss * (1.0f / 1024.0f) + EPS);
;         const float* mr = modl + (size_t)r * 6144;
; #pragma unroll
;         for (int i = 0; i < 4; ++i) {
;             const int k = i * 256 + lane * 4;
;             const float4 gg = *(const float4*)(g + k), scv = *(const float4*)(mr + sc_off + k), shv = *(const float4*)(mr + sh_off + k);
;             const float o0 = v[i].x * rstd * gg.x * (1.0f + scv.x) + shv.x, o1 = v[i].y * rstd * gg.y * (1.0f + scv.y) + shv.y;
;             const float o2 = v[i].z * rstd * gg.z * (1.0f + scv.z) + shv.z, o3 = v[i].w * rstd * gg.w * (1.0f + scv.w) + shv.w;
;             uint2 w; w.x = pk2(o0, o1); w.y = pk2(o2, o3);
;             *(uint2*)(A + (size_t)row * 1024 + k) = w;
;         }
; #pragma unroll
;         for (int i = 0; i < 4; ++i) v[i] = nv[i];
;         row = nrow;
;     }
	v_add_f32_e32 v204, v204, v205
	v_mov_b32_e32 v205, v204
	s_nop 1
	v_permlane32_swap_b32_e32 v204, v205
	v_add_f32_e32 v204, v204, v205
	v_mov_b32_e32 v205, 0x358637bd
	v_fmamk_f32 v204, v204, 0x3a800000, v205
	v_rsq_f32_e32 v204, v204
	s_nop 0
	v_pk_mul_f32 v[80:81], v[80:81], v[204:205] op_sel_hi:[1,0]
	v_pk_mul_f32 v[82:83], v[82:83], v[204:205] op_sel_hi:[1,0]
	v_pk_mul_f32 v[80:81], v[188:189], v[80:81]
	v_pk_mul_f32 v[82:83], v[190:191], v[82:83]
	v_pk_fma_f32 v[80:81], v[34:35], v[80:81], v[224:225]
	v_pk_fma_f32 v[82:83], v[36:37], v[82:83], v[226:227]
	v_cvt_pk_bf16_f32 v80, v80, v81
	v_cvt_pk_bf16_f32 v81, v82, v83
	global_store_dwordx2 v146, v[80:81], s[66:67]
	v_pk_mul_f32 v[84:85], v[84:85], v[204:205] op_sel_hi:[1,0]
	v_pk_mul_f32 v[86:87], v[86:87], v[204:205] op_sel_hi:[1,0]
	v_pk_mul_f32 v[84:85], v[192:193], v[84:85]
	v_pk_mul_f32 v[86:87], v[194:195], v[86:87]
	v_pk_fma_f32 v[84:85], v[38:39], v[84:85], v[228:229]
	v_pk_fma_f32 v[86:87], v[40:41], v[86:87], v[230:231]
	v_cvt_pk_bf16_f32 v84, v84, v85
	v_cvt_pk_bf16_f32 v85, v86, v87
	global_store_dwordx2 v146, v[84:85], s[66:67] offset:512
	v_pk_mul_f32 v[88:89], v[88:89], v[204:205] op_sel_hi:[1,0]
	v_pk_mul_f32 v[90:91], v[90:91], v[204:205] op_sel_hi:[1,0]
	v_pk_mul_f32 v[88:89], v[196:197], v[88:89]
	v_pk_mul_f32 v[90:91], v[198:199], v[90:91]
	v_pk_fma_f32 v[88:89], v[42:43], v[88:89], v[232:233]
	v_pk_fma_f32 v[90:91], v[44:45], v[90:91], v[234:235]
	v_cvt_pk_bf16_f32 v88, v88, v89
	v_cvt_pk_bf16_f32 v89, v90, v91
	global_store_dwordx2 v146, v[88:89], s[66:67] offset:1024
	v_pk_mul_f32 v[92:93], v[92:93], v[204:205] op_sel_hi:[1,0]
	v_pk_mul_f32 v[94:95], v[94:95], v[204:205] op_sel_hi:[1,0]
	v_pk_mul_f32 v[92:93], v[200:201], v[92:93]
	v_pk_mul_f32 v[94:95], v[202:203], v[94:95]
	v_pk_fma_f32 v[92:93], v[46:47], v[92:93], v[236:237]
	v_pk_fma_f32 v[94:95], v[48:49], v[94:95], v[238:239]
	v_cvt_pk_bf16_f32 v92, v92, v93
	v_cvt_pk_bf16_f32 v93, v94, v95
	global_store_dwordx2 v146, v[92:93], s[66:67] offset:1536
	v_add_u32_e32 v146, 0x800, v146
	s_waitcnt vmcnt(28)
	v_pk_mul_f32 v[242:243], v[96:97], v[96:97]
	v_pk_mul_f32 v[244:245], v[100:101], v[100:101]
	v_pk_mul_f32 v[246:247], v[98:99], v[98:99]
	v_pk_mul_f32 v[248:249], v[102:103], v[102:103]
	v_add_f32_e32 v204, v245, v244
	v_add_f32_e32 v205, v243, v242
	v_add_f32_e32 v204, v248, v204
	v_add_f32_e32 v205, v246, v205
	v_add_f32_e32 v204, v249, v204
	v_add_f32_e32 v205, v247, v205
	v_pk_mul_f32 v[242:243], v[104:105], v[104:105]
	v_pk_mul_f32 v[244:245], v[108:109], v[108:109]
	v_pk_mul_f32 v[246:247], v[106:107], v[106:107]
	v_pk_mul_f32 v[248:249], v[110:111], v[110:111]
	v_add_f32_e32 v206, v243, v242
	v_add_f32_e32 v207, v245, v244
	v_add_f32_e32 v206, v246, v206
	v_add_f32_e32 v207, v248, v207
	v_add_f32_e32 v206, v247, v206
	v_add_f32_e32 v207, v249, v207
	v_add_f32_e32 v204, v205, v204
	v_add_f32_e32 v204, v204, v206
	v_add_f32_e32 v204, v204, v207
	ds_swizzle_b32 v205, v204 offset:swizzle(SWAP,1)
	s_waitcnt lgkmcnt(0)
	v_add_f32_e32 v204, v204, v205
	ds_swizzle_b32 v205, v204 offset:swizzle(SWAP,2)
	s_waitcnt lgkmcnt(0)
	v_add_f32_e32 v204, v204, v205
	ds_swizzle_b32 v205, v204 offset:swizzle(SWAP,4)
	s_waitcnt lgkmcnt(0)
	v_add_f32_e32 v204, v204, v205
	ds_swizzle_b32 v205, v204 offset:swizzle(SWAP,8)
	s_waitcnt lgkmcnt(0)
	v_add_f32_e32 v204, v204, v205
	ds_swizzle_b32 v205, v204 offset:swizzle(SWAP,16)
	s_waitcnt lgkmcnt(0)
	v_add_f32_e32 v204, v204, v205
	v_mov_b32_e32 v205, v204
	s_nop 1
	v_permlane32_swap_b32_e32 v204, v205
	v_add_f32_e32 v204, v204, v205
	v_mov_b32_e32 v205, 0x358637bd
	v_fmamk_f32 v204, v204, 0x3a800000, v205
	v_rsq_f32_e32 v204, v204
	s_nop 0
	v_pk_mul_f32 v[96:97], v[96:97], v[204:205] op_sel_hi:[1,0]
	v_pk_mul_f32 v[98:99], v[98:99], v[204:205] op_sel_hi:[1,0]
	v_pk_mul_f32 v[96:97], v[188:189], v[96:97]
	v_pk_mul_f32 v[98:99], v[190:191], v[98:99]
	v_pk_fma_f32 v[96:97], v[34:35], v[96:97], v[224:225]
	v_pk_fma_f32 v[98:99], v[36:37], v[98:99], v[226:227]
	v_cvt_pk_bf16_f32 v96, v96, v97
	v_cvt_pk_bf16_f32 v97, v98, v99
	global_store_dwordx2 v146, v[96:97], s[66:67]
	v_pk_mul_f32 v[100:101], v[100:101], v[204:205] op_sel_hi:[1,0]
	v_pk_mul_f32 v[102:103], v[102:103], v[204:205] op_sel_hi:[1,0]
	v_pk_mul_f32 v[100:101], v[192:193], v[100:101]
	v_pk_mul_f32 v[102:103], v[194:195], v[102:103]
	v_pk_fma_f32 v[100:101], v[38:39], v[100:101], v[228:229]
	v_pk_fma_f32 v[102:103], v[40:41], v[102:103], v[230:231]
	v_cvt_pk_bf16_f32 v100, v100, v101
	v_cvt_pk_bf16_f32 v101, v102, v103
	global_store_dwordx2 v146, v[100:101], s[66:67] offset:512
	v_pk_mul_f32 v[104:105], v[104:105], v[204:205] op_sel_hi:[1,0]
	v_pk_mul_f32 v[106:107], v[106:107], v[204:205] op_sel_hi:[1,0]
	v_pk_mul_f32 v[104:105], v[196:197], v[104:105]
	v_pk_mul_f32 v[106:107], v[198:199], v[106:107]
	v_pk_fma_f32 v[104:105], v[42:43], v[104:105], v[232:233]
	v_pk_fma_f32 v[106:107], v[44:45], v[106:107], v[234:235]
	v_cvt_pk_bf16_f32 v104, v104, v105
	v_cvt_pk_bf16_f32 v105, v106, v107
	global_store_dwordx2 v146, v[104:105], s[66:67] offset:1024
	v_pk_mul_f32 v[108:109], v[108:109], v[204:205] op_sel_hi:[1,0]
	v_pk_mul_f32 v[110:111], v[110:111], v[204:205] op_sel_hi:[1,0]
	v_pk_mul_f32 v[108:109], v[200:201], v[108:109]
	v_pk_mul_f32 v[110:111], v[202:203], v[110:111]
	v_pk_fma_f32 v[108:109], v[46:47], v[108:109], v[236:237]
	v_pk_fma_f32 v[110:111], v[48:49], v[110:111], v[238:239]
	v_cvt_pk_bf16_f32 v108, v108, v109
	v_cvt_pk_bf16_f32 v109, v110, v111
	global_store_dwordx2 v146, v[108:109], s[66:67] offset:1536
	v_add_u32_e32 v146, 0x800, v146
	s_waitcnt vmcnt(24)
; __device__ __forceinline__ unsigned pk2(float lo, float hi) { const g_f32x2 f = {lo, hi}; return __builtin_bit_cast(unsigned, __builtin_convertvector(f, g_bf16x2)); }
; __device__ __forceinline__ void p_norm(const float* hlat, const float* hctx, const float* g, const float* modl, int sh_off, int sc_off, bf16_t* A, int M,
;                                        const float* part, const float* cgate, float* hcout) {
;     ...
;         float ss = 0.f;
; #pragma unroll
;         for (int i = 0; i < 4; ++i) {
;             if (part != nullptr && row >= NLAT) {
;                 const size_t po = (size_t)(row - NLAT) * 1024 + i * 256 + lane * 4;
;                 const float4 p0 = *(const float4*)(part + po), p1 = *(const float4*)(part + (size_t)4096 * 1024 + po), cg = *(const float4*)(cgate + i * 256 + lane * 4);
;                 v[i].x += cg.x * (p0.x + p1.x); v[i].y += cg.y * (p0.y + p1.y); v[i].z += cg.z * (p0.z + p1.z); v[i].w += cg.w * (p0.w + p1.w);
;                 *(float4*)(hcout + po) = v[i];
;             }
;             ss += v[i].x * v[i].x + v[i].y * v[i].y + v[i].z * v[i].z + v[i].w * v[i].w; }
;         ss = wave_sum(ss);
;         const float rstd = rsqrtf(ss * (1.0f / 1024.0f) + EPS);
;         const float* mr = modl + (size_t)r * 6144;
; #pragma unroll
;         for (int i = 0; i < 4; ++i) {
;             const int k = i * 256 + lane * 4;
;             const float4 gg = *(const float4*)(g + k), scv = *(const float4*)(mr + sc_off + k), shv = *(const float4*)(mr + sh_off + k);
;             const float o0 = v[i].x * rstd * gg.x * (1.0f + scv.x) + shv.x, o1 = v[i].y * rstd * gg.y * (1.0f + scv.y) + shv.y;
;             const float o2 = v[i].z * rstd * gg.z * (1.0f + scv.z) + shv.z, o3 = v[i].w * rstd * gg.w * (1.0f + scv.w) + shv.w;
;             uint2 w; w.x = pk2(o0, o1); w.y = pk2(o2, o3);
;             *(uint2*)(A + (size_t)row * 1024 + k) = w;
;         }
; #pragma unroll
;         for (int i = 0; i < 4; ++i) v[i] = nv[i];
;         row = nrow;
;     }
	v_pk_mul_f32 v[242:243], v[112:113], v[112:113]
	v_pk_mul_f32 v[244:245], v[116:117], v[116:117]
	v_pk_mul_f32 v[246:247], v[114:115], v[114:115]
	v_pk_mul_f32 v[248:249], v[118:119], v[118:119]
	v_add_f32_e32 v204, v245, v244
	v_add_f32_e32 v205, v243, v242
	v_add_f32_e32 v204, v248, v204
	v_add_f32_e32 v205, v246, v205
	v_add_f32_e32 v204, v249, v204
	v_add_f32_e32 v205, v247, v205
	v_pk_mul_f32 v[242:243], v[120:121], v[120:121]
	v_pk_mul_f32 v[244:245], v[124:125], v[124:125]
	v_pk_mul_f32 v[246:247], v[122:123], v[122:123]
	v_pk_mul_f32 v[248:249], v[126:127], v[126:127]
	v_add_f32_e32 v206, v243, v242
	v_add_f32_e32 v207, v245, v244
	v_add_f32_e32 v206, v246, v206
	v_add_f32_e32 v207, v248, v207
	v_add_f32_e32 v206, v247, v206
	v_add_f32_e32 v207, v249, v207
	v_add_f32_e32 v204, v205, v204
	v_add_f32_e32 v204, v204, v206
	v_add_f32_e32 v204, v204, v207
	ds_swizzle_b32 v205, v204 offset:swizzle(SWAP,1)
	s_waitcnt lgkmcnt(0)
	v_add_f32_e32 v204, v204, v205
	ds_swizzle_b32 v205, v204 offset:swizzle(SWAP,2)
	s_waitcnt lgkmcnt(0)
	v_add_f32_e32 v204, v204, v205
	ds_swizzle_b32 v205, v204 offset:swizzle(SWAP,4)
	s_waitcnt lgkmcnt(0)
	v_add_f32_e32 v204, v204, v205
	ds_swizzle_b32 v205, v204 offset:swizzle(SWAP,8)
	s_waitcnt lgkmcnt(0)
	v_add_f32_e32 v204, v204, v205
	ds_swizzle_b32 v205, v204 offset:swizzle(SWAP,16)
	s_waitcnt lgkmcnt(0)
	v_add_f32_e32 v204, v204, v205
	v_mov_b32_e32 v205, v204
	s_nop 1
	v_permlane32_swap_b32_e32 v204, v205
	v_add_f32_e32 v204, v204, v205
	v_mov_b32_e32 v205, 0x358637bd
	v_fmamk_f32 v204, v204, 0x3a800000, v205
	v_rsq_f32_e32 v204, v204
	s_nop 0
	v_pk_mul_f32 v[112:113], v[112:113], v[204:205] op_sel_hi:[1,0]
	v_pk_mul_f32 v[114:115], v[114:115], v[204:205] op_sel_hi:[1,0]
	v_pk_mul_f32 v[112:113], v[188:189], v[112:113]
	v_pk_mul_f32 v[114:115], v[190:191], v[114:115]
	v_pk_fma_f32 v[112:113], v[34:35], v[112:113], v[224:225]
	v_pk_fma_f32 v[114:115], v[36:37], v[114:115], v[226:227]
	v_cvt_pk_bf16_f32 v112, v112, v113
	v_cvt_pk_bf16_f32 v113, v114, v115
	global_store_dwordx2 v146, v[112:113], s[66:67]
	v_pk_mul_f32 v[116:117], v[116:117], v[204:205] op_sel_hi:[1,0]
	v_pk_mul_f32 v[118:119], v[118:119], v[204:205] op_sel_hi:[1,0]
	v_pk_mul_f32 v[116:117], v[192:193], v[116:117]
	v_pk_mul_f32 v[118:119], v[194:195], v[118:119]
	v_pk_fma_f32 v[116:117], v[38:39], v[116:117], v[228:229]
	v_pk_fma_f32 v[118:119], v[40:41], v[118:119], v[230:231]
	v_cvt_pk_bf16_f32 v116, v116, v117
	v_cvt_pk_bf16_f32 v117, v118, v119
	global_store_dwordx2 v146, v[116:117], s[66:67] offset:512
	v_pk_mul_f32 v[120:121], v[120:121], v[204:205] op_sel_hi:[1,0]
	v_pk_mul_f32 v[122:123], v[122:123], v[204:205] op_sel_hi:[1,0]
	v_pk_mul_f32 v[120:121], v[196:197], v[120:121]
	v_pk_mul_f32 v[122:123], v[198:199], v[122:123]
	v_pk_fma_f32 v[120:121], v[42:43], v[120:121], v[232:233]
	v_pk_fma_f32 v[122:123], v[44:45], v[122:123], v[234:235]
	v_cvt_pk_bf16_f32 v120, v120, v121
	v_cvt_pk_bf16_f32 v121, v122, v123
	global_store_dwordx2 v146, v[120:121], s[66:67] offset:1024
	v_pk_mul_f32 v[124:125], v[124:125], v[204:205] op_sel_hi:[1,0]
	v_pk_mul_f32 v[126:127], v[126:127], v[204:205] op_sel_hi:[1,0]
	v_pk_mul_f32 v[124:125], v[200:201], v[124:125]
	v_pk_mul_f32 v[126:127], v[202:203], v[126:127]
	v_pk_fma_f32 v[124:125], v[46:47], v[124:125], v[236:237]
	v_pk_fma_f32 v[126:127], v[48:49], v[126:127], v[238:239]
	v_cvt_pk_bf16_f32 v124, v124, v125
	v_cvt_pk_bf16_f32 v125, v126, v127
	global_store_dwordx2 v146, v[124:125], s[66:67] offset:1536
	v_add_u32_e32 v146, 0x800, v146
	s_waitcnt vmcnt(20)
; __device__ __forceinline__ unsigned pk2(float lo, float hi) { const g_f32x2 f = {lo, hi}; return __builtin_bit_cast(unsigned, __builtin_convertvector(f, g_bf16x2)); }
; #define PG8_WAIT_V(n) asm volatile("s_waitcnt vmcnt(" #n ")" ::: "memory")
; #define PG8_BAR __builtin_amdgcn_s_barrier()
; template <class Epi, class Sched>
; __device__ __forceinline__ void gemm_phase(PG8_LAS unsigned char* lds, const Gemm g, const Sched& S, const Epi& E) {
;     ...
;     PG8_WAIT_V(0);
;     if (wr == 0) PG8_BAR;
;     PG8_BAR;
; __device__ __forceinline__ void p_norm(const float* hlat, const float* hctx, const float* g, const float* modl, int sh_off, int sc_off, bf16_t* A, int M,
;                                        const float* part, const float* cgate, float* hcout) {
;     ...
;         float ss = 0.f;
; #pragma unroll
;         for (int i = 0; i < 4; ++i) {
;             if (part != nullptr && row >= NLAT) {
;                 const size_t po = (size_t)(row - NLAT) * 1024 + i * 256 + lane * 4;
;                 const float4 p0 = *(const float4*)(part + po), p1 = *(const float4*)(part + (size_t)4096 * 1024 + po), cg = *(const float4*)(cgate + i * 256 + lane * 4);
;                 v[i].x += cg.x * (p0.x + p1.x); v[i].y += cg.y * (p0.y + p1.y); v[i].z += cg.z * (p0.z + p1.z); v[i].w += cg.w * (p0.w + p1.w);
;                 *(float4*)(hcout + po) = v[i];
;             }
;             ss += v[i].x * v[i].x + v[i].y * v[i].y + v[i].z * v[i].z + v[i].w * v[i].w; }
;         ss = wave_sum(ss);
;         const float rstd = rsqrtf(ss * (1.0f / 1024.0f) + EPS);
;         const float* mr = modl + (size_t)r * 6144;
; #pragma unroll
;         for (int i = 0; i < 4; ++i) {
;             const int k = i * 256 + lane * 4;
;             const float4 gg = *(const float4*)(g + k), scv = *(const float4*)(mr + sc_off + k), shv = *(const float4*)(mr + sh_off + k);
;             const float o0 = v[i].x * rstd * gg.x * (1.0f + scv.x) + shv.x, o1 = v[i].y * rstd * gg.y * (1.0f + scv.y) + shv.y;
;             const float o2 = v[i].z * rstd * gg.z * (1.0f + scv.z) + shv.z, o3 = v[i].w * rstd * gg.w * (1.0f + scv.w) + shv.w;
;             uint2 w; w.x = pk2(o0, o1); w.y = pk2(o2, o3);
;             *(uint2*)(A + (size_t)row * 1024 + k) = w;
;         }
; #pragma unroll
;         for (int i = 0; i < 4; ++i) v[i] = nv[i];
;         row = nrow;
;     }
	v_pk_mul_f32 v[242:243], v[128:129], v[128:129]
	v_pk_mul_f32 v[244:245], v[132:133], v[132:133]
	v_pk_mul_f32 v[246:247], v[130:131], v[130:131]
	v_pk_mul_f32 v[248:249], v[134:135], v[134:135]
	v_add_f32_e32 v204, v245, v244
	v_add_f32_e32 v205, v243, v242
	v_add_f32_e32 v204, v248, v204
	v_add_f32_e32 v205, v246, v205
	v_add_f32_e32 v204, v249, v204
	v_add_f32_e32 v205, v247, v205
	v_pk_mul_f32 v[242:243], v[136:137], v[136:137]
	v_pk_mul_f32 v[244:245], v[140:141], v[140:141]
	v_pk_mul_f32 v[246:247], v[138:139], v[138:139]
	v_pk_mul_f32 v[248:249], v[142:143], v[142:143]
	v_add_f32_e32 v206, v243, v242
	v_add_f32_e32 v207, v245, v244
	v_add_f32_e32 v206, v246, v206
	v_add_f32_e32 v207, v248, v207
	v_add_f32_e32 v206, v247, v206
	v_add_f32_e32 v207, v249, v207
	v_add_f32_e32 v204, v205, v204
	v_add_f32_e32 v204, v204, v206
	v_add_f32_e32 v204, v204, v207
	ds_swizzle_b32 v205, v204 offset:swizzle(SWAP,1)
	s_waitcnt lgkmcnt(0)
	v_add_f32_e32 v204, v204, v205
	ds_swizzle_b32 v205, v204 offset:swizzle(SWAP,2)
	s_waitcnt lgkmcnt(0)
	v_add_f32_e32 v204, v204, v205
	ds_swizzle_b32 v205, v204 offset:swizzle(SWAP,4)
	s_waitcnt lgkmcnt(0)
	v_add_f32_e32 v204, v204, v205
	ds_swizzle_b32 v205, v204 offset:swizzle(SWAP,8)
	s_waitcnt lgkmcnt(0)
	v_add_f32_e32 v204, v204, v205
	ds_swizzle_b32 v205, v204 offset:swizzle(SWAP,16)
	s_waitcnt lgkmcnt(0)
	v_add_f32_e32 v204, v204, v205
	v_mov_b32_e32 v205, v204
	s_nop 1
	v_permlane32_swap_b32_e32 v204, v205
	v_add_f32_e32 v204, v204, v205
	v_mov_b32_e32 v205, 0x358637bd
	v_fmamk_f32 v204, v204, 0x3a800000, v205
	v_rsq_f32_e32 v204, v204
	s_nop 0
	v_pk_mul_f32 v[128:129], v[128:129], v[204:205] op_sel_hi:[1,0]
	v_pk_mul_f32 v[130:131], v[130:131], v[204:205] op_sel_hi:[1,0]
	v_pk_mul_f32 v[128:129], v[188:189], v[128:129]
	v_pk_mul_f32 v[130:131], v[190:191], v[130:131]
	v_pk_fma_f32 v[128:129], v[34:35], v[128:129], v[224:225]
	v_pk_fma_f32 v[130:131], v[36:37], v[130:131], v[226:227]
	v_cvt_pk_bf16_f32 v128, v128, v129
	v_cvt_pk_bf16_f32 v129, v130, v131
	global_store_dwordx2 v146, v[128:129], s[66:67]
	v_pk_mul_f32 v[132:133], v[132:133], v[204:205] op_sel_hi:[1,0]
	v_pk_mul_f32 v[134:135], v[134:135], v[204:205] op_sel_hi:[1,0]
	v_pk_mul_f32 v[132:133], v[192:193], v[132:133]
	v_pk_mul_f32 v[134:135], v[194:195], v[134:135]
	v_pk_fma_f32 v[132:133], v[38:39], v[132:133], v[228:229]
	v_pk_fma_f32 v[134:135], v[40:41], v[134:135], v[230:231]
	v_cvt_pk_bf16_f32 v132, v132, v133
	v_cvt_pk_bf16_f32 v133, v134, v135
	global_store_dwordx2 v146, v[132:133], s[66:67] offset:512
	v_pk_mul_f32 v[136:137], v[136:137], v[204:205] op_sel_hi:[1,0]
	v_pk_mul_f32 v[138:139], v[138:139], v[204:205] op_sel_hi:[1,0]
	v_pk_mul_f32 v[136:137], v[196:197], v[136:137]
	v_pk_mul_f32 v[138:139], v[198:199], v[138:139]
	v_pk_fma_f32 v[136:137], v[42:43], v[136:137], v[232:233]
	v_pk_fma_f32 v[138:139], v[44:45], v[138:139], v[234:235]
	v_cvt_pk_bf16_f32 v136, v136, v137
	v_cvt_pk_bf16_f32 v137, v138, v139
	global_store_dwordx2 v146, v[136:137], s[66:67] offset:1024
	v_pk_mul_f32 v[140:141], v[140:141], v[204:205] op_sel_hi:[1,0]
	v_pk_mul_f32 v[142:143], v[142:143], v[204:205] op_sel_hi:[1,0]
	v_pk_mul_f32 v[140:141], v[200:201], v[140:141]
	v_pk_mul_f32 v[142:143], v[202:203], v[142:143]
	v_pk_fma_f32 v[140:141], v[46:47], v[140:141], v[236:237]
	v_pk_fma_f32 v[142:143], v[48:49], v[142:143], v[238:239]
	v_cvt_pk_bf16_f32 v140, v140, v141
	v_cvt_pk_bf16_f32 v141, v142, v143
	global_store_dwordx2 v146, v[140:141], s[66:67] offset:1536
	v_add_u32_e32 v146, 0x800, v146
	s_add_i32 s97, s97, 1
	s_cmp_lt_u32 s97, 2
	s_cbranch_scc1 .Lfz_pass
.Lfz_skip:
.LBB0_1205:
	s_waitcnt vmcnt(0)
	s_waitcnt vmcnt(0) lgkmcnt(0)
	s_barrier
	s_and_saveexec_b64 s[2:3], s[12:13]
	s_mov_b32 s10, 0x9000
	s_mov_b32 s11, 0x8fff
	s_cbranch_execz .Lhop_403
	v_readlane_b32 s5, v255, 27
	s_waitcnt vmcnt(0) expcnt(0) lgkmcnt(0)
	s_nop 0
	v_mov_b32_e32 v1, s5
	ds_read_b32 v3, v1
	v_readlane_b32 s5, v255, 28
	s_waitcnt lgkmcnt(0)
	v_cmp_ne_u32_e32 vcc, 0, v3
	v_mov_b32_e32 v1, s5
	ds_read_b32 v2, v1
	s_cbranch_vccnz .LBB0_1221
	s_mov_b32 s5, 1
	s_branch .LBB0_1209
